# both attention phases (GQA and MLA) hand-scheduled and software-pipelined; row-sum cross-lane reduction done exactly
# speedup vs baseline: 1.0249x; 1.0065x over previous
; template <bool MLA>
; DI void attn_phase(const int TID, const int BID, LAS unsigned char* lds, const Params& p, bool need_ctx) {
;     ...
;     const int tid = TID, wid = tid >> 6, lane = tid & 63, r = lane & 31, hh = lane >> 5;
;     const int n_items = 1024 + (need_ctx ? 128 : 0);
;     bf16_t* O = P_WSB(OFF_H);
;     for (int item = BID; item < n_items; item += gridDim.x) {
;         int b, head, row0, nk;
;         if (item < 1024) {
;             const int rnd = item >> 8, w = item & 255, xcd = w & 7, slot = w >> 3, qb = slot & 7;
;             if (MLA) { const int grp = (rnd * 8 + xcd) * 4 + (slot >> 3); b = grp >> 4; head = grp & 15; }
;             else { const int grp = rnd * 8 + xcd; b = grp >> 2; head = (grp & 3) * 4 + (slot >> 3); }
;             row0 = b * 2048 + qb * 256; nk = NKEY;
;         }
;         else { const int it = item - 1024; b = it >> 4; head = it & 15; row0 = TL + b * 256; nk = 256; }
;         const int kvh = MLA ? head : (head >> 2);
;         const bf16_t* Kb = P_WSB(OFF_K) + (size_t)(b * NKV + kvh) * NKEY * 64;
;         const bf16_t* Vb = P_WSB(OFF_VT) + (size_t)(b * NKV + kvh) * NKEY * 64;
;         const bf16_t* Pb = P_WSB(OFF_KPE) + (size_t)b * NKEY * 32;
;         bf16x8 qf[NKS];
;         {
;             const bf16_t* qp = P_WSB(OFF_Q) + (size_t)(row0 + wid * 32 + r) * QS + head * DK + hh * 8;
; #pragma unroll
;             for (int ks = 0; ks < NKS; ++ks) qf[ks] = *(const bf16x8*)(qp + ks * 16);
;         }
;         u32x4 kreg, vreg; u32x2 preg = {0u, 0u};
.LBB0_293:
	s_andn2_b64 vcc, exec, s[0:1]
	s_cbranch_vccnz .LBB0_773
	s_add_i32 s0, s23, 0x22040
	v_writelane_b32 v255, s0, 32
	s_nop 0
	v_readlane_b32 s0, v255, 21
	s_cmp_lt_i32 s0, 2
	s_mov_b64 s[0:1], -1
	s_cbranch_scc1 .LBB0_501
	v_readlane_b32 s0, v255, 21
	s_cmp_gt_i32 s0, 2
	v_readlane_b32 s0, v255, 24
	v_readlane_b32 s1, v255, 25
	s_mov_b64 s[2:3], -1
	s_nop 0
	v_cndmask_b32_e64 v0, 0, 1, s[0:1]
	v_cmp_ne_u32_e64 s[0:1], 1, v0
	s_cbranch_scc0 .LBB0_340
	v_readlane_b32 s2, v255, 27
	s_cmp_lt_i32 s2, 3
	s_movk_i32 s2, 0x480
	s_cselect_b32 s8, s2, 0x400
	v_readlane_b32 s3, v255, 28
	s_cmp_lt_i32 s83, s8
	s_cselect_b64 s[2:3], -1, 0
	v_cndmask_b32_e64 v0, 0, 1, s[2:3]
	s_mov_b64 s[4:5], -1
	s_and_b64 vcc, exec, s[0:1]
	v_cmp_ne_u32_e64 s[2:3], 1, v0
	s_cbranch_vccnz .LBB0_318
	s_and_b64 vcc, exec, s[2:3]
	s_cbranch_vccnz .LBB0_317
	v_and_b32_e32 v230, 31, v174
	v_bfe_u32 v231, v174, 5, 1
	v_lshrrev_b32_e32 v232, 6, v174
	v_lshrrev_b32_e32 v233, 3, v174
	v_and_b32_e32 v234, 7, v174
	v_mov_b32_e32 v235, s23
	s_movk_i32 s15, 0xd0
	v_mad_u32_u24 v229, v230, s15, v235
	v_lshl_add_u32 v229, v231, 4, v229
	v_mad_u32_u24 v218, v233, s15, v235
	v_lshl_add_u32 v219, v234, 3, v218
	v_add_u32_e32 v219, 0x80, v219
	v_lshl_add_u32 v218, v234, 4, v218
	s_movk_i32 s15, 0xc0
	v_bfe_u32 v236, v174, 2, 2
	v_lshl_add_u32 v236, v231, 2, v236
	v_mad_u32_u24 v220, v236, s15, v235
	v_bfe_u32 v237, v174, 4, 1
	v_and_b32_e32 v238, 3, v174
	v_lshlrev_b32_e32 v237, 5, v237
	v_lshl_add_u32 v237, v238, 3, v237
	v_add_u32_e32 v220, v220, v237
	v_add_u32_e32 v220, 0x6800, v220
	v_mad_u32_u24 v221, v233, s15, v235
	v_lshl_add_u32 v221, v234, 4, v221
	v_add_u32_e32 v221, 0x6800, v221
	v_lshlrev_b32_e32 v225, 7, v233
	v_lshl_add_u32 v225, v234, 4, v225
	v_lshlrev_b32_e32 v226, 6, v233
	v_lshl_add_u32 v226, v234, 3, v226
	v_lshl_add_u32 v239, v232, 5, v230
	s_movk_i32 s15, 0xc00
	v_mul_u32_u24_e32 v227, s15, v239
	v_lshl_add_u32 v227, v231, 4, v227
	v_lshlrev_b32_e32 v228, 11, v239
	v_lshl_add_u32 v228, v231, 4, v228
	v_mov_b32_e32 v167, 0
	v_readfirstlane_b32 s58, v232
	s_mov_b32 s6, s83
	s_lshr_b32 s58, s58, 2

; #define AT_GLOADK(k0) do { kreg = *(const u32x4*)(Kb + (size_t)((k0) + (tid >> 3)) * 64 + (tid & 7) * 8); \
;             if (MLA) preg = *(const u32x2*)(Pb + (size_t)((k0) + (tid >> 3)) * 32 + (tid & 7) * 4); } while (0)
; #define AT_GLOADV(k0) do { vreg = *(const u32x4*)(Vb + (size_t)((k0) + (tid >> 3)) * 64 + (tid & 7) * 8); } while (0)
; #define AT_WRITEK(buf) do { *(LAS u32x4*)(lds + (buf) * KBUF + (tid >> 3) * KSTR + (tid & 7) * 16) = kreg; \
;             if (MLA) *(LAS u32x2*)(lds + (buf) * KBUF + (tid >> 3) * KSTR + 128 + (tid & 7) * 8) = preg; } while (0)
; #define AT_WRITEV(buf) do { *(LAS u32x4*)(lds + 2 * KBUF + (buf) * VBUF + (tid >> 3) * VSTR + (tid & 7) * 16) = vreg; } while (0)
; template <bool MLA>
; DI void attn_phase(const int TID, const int BID, LAS unsigned char* lds, const Params& p, bool need_ctx) {
;     ...
;             const int rnd = item >> 8, w = item & 255, xcd = w & 7, slot = w >> 3, qb = slot & 7;
;             if (MLA) { const int grp = (rnd * 8 + xcd) * 4 + (slot >> 3); b = grp >> 4; head = grp & 15; }
;             else { const int grp = rnd * 8 + xcd; b = grp >> 2; head = (grp & 3) * 4 + (slot >> 3); }
;             row0 = b * 2048 + qb * 256; nk = NKEY;
;         }
;         else { const int it = item - 1024; b = it >> 4; head = it & 15; row0 = TL + b * 256; nk = 256; }
;         const int kvh = MLA ? head : (head >> 2);
;         const bf16_t* Kb = P_WSB(OFF_K) + (size_t)(b * NKV + kvh) * NKEY * 64;
;         const bf16_t* Vb = P_WSB(OFF_VT) + (size_t)(b * NKV + kvh) * NKEY * 64;
;         const bf16_t* Pb = P_WSB(OFF_KPE) + (size_t)b * NKEY * 32;
;         bf16x8 qf[NKS];
;         {
;             const bf16_t* qp = P_WSB(OFF_Q) + (size_t)(row0 + wid * 32 + r) * QS + head * DK + hh * 8;
; #pragma unroll
;             for (int ks = 0; ks < NKS; ++ks) qf[ks] = *(const bf16x8*)(qp + ks * 16);
;         }
;         u32x4 kreg, vreg; u32x2 preg = {0u, 0u};
;     ...
;         f32x16 o0, o1, sa0, sa1, sb0, sb1;
; #pragma unroll
;         for (int j = 0; j < 16; ++j) { o0[j] = 0.f; o1[j] = 0.f; }
;         float mrun = -1e30f, lsum = 0.f;
;         if (wid >= 4) __builtin_amdgcn_s_setprio(1);
;         const int ntile = nk >> 6;
;         AT_GLOADK(0); AT_GLOADV(0); AT_WRITEK(0); AT_WRITEV(0);
;         AT_GLOADK(64); AT_WRITEK(1);
;         __syncthreads();
;         AT_QK(sa0, sa1, 0);
;         __syncthreads();
.Lamla_mainitem:
	s_lshr_b32 s21, s6, 8
	s_and_b32 s55, s6, 7
	s_lshl_b32 s21, s21, 3
	s_add_i32 s21, s21, s55
	s_bfe_u32 s55, s6, 0x30003
	s_bfe_u32 s56, s6, 0x20006
	s_lshl_b32 s21, s21, 2
	s_add_i32 s21, s21, s56
	s_lshr_b32 s15, s21, 4
	s_and_b32 s18, s21, 15
	s_lshl_b32 s20, s15, 11
	s_lshl_b32 s55, s55, 8
	s_add_i32 s20, s20, s55
	s_mov_b32 s7, 16
.Lamla_decoded:
	s_mov_b32 s19, s18
	s_lshl_b32 s21, s15, 4
	s_add_i32 s21, s21, s19
	s_mul_i32 s21, s21, 0x48000
	s_add_u32 s2, s26, s21
	s_addc_u32 s3, s27, 0
	v_readlane_b32 s60, v254, 36
	v_readlane_b32 s61, v254, 37
	s_add_u32 s4, s60, s21
	s_addc_u32 s5, s61, 0
	v_readlane_b32 s60, v254, 38
	v_readlane_b32 s61, v254, 39
	s_mul_i32 s21, s15, 0x24000
	s_add_u32 s10, s60, s21
	s_addc_u32 s11, s61, 0
	v_readlane_b32 s60, v254, 27
	v_readlane_b32 s61, v254, 28
	s_mul_i32 s21, s20, 0xc00
	s_mul_i32 s55, s18, 0xc0
	s_add_i32 s21, s21, s55
	s_add_u32 s12, s60, s21
	s_addc_u32 s13, s61, 0
	v_readlane_b32 s60, v254, 34
	v_readlane_b32 s61, v254, 35
	s_lshl_b32 s21, s20, 11
	s_lshl_b32 s55, s18, 7
	s_add_i32 s21, s21, s55
	s_add_u32 s16, s60, s21
	s_addc_u32 s17, s61, 0
	global_load_dwordx4 v[112:115], v227, s[12:13]
	global_load_dwordx4 v[116:119], v227, s[12:13] offset:32
	global_load_dwordx4 v[120:123], v227, s[12:13] offset:64
	global_load_dwordx4 v[124:127], v227, s[12:13] offset:96
	global_load_dwordx4 v[128:131], v227, s[12:13] offset:128
	global_load_dwordx4 v[132:135], v227, s[12:13] offset:160
	global_load_dwordx4 v[136:139], v225, s[2:3]
	global_load_dwordx2 v[230:231], v226, s[10:11]
	s_add_u32 s2, s2, 0x2000
	s_addc_u32 s3, s3, 0
	s_add_u32 s10, s10, 0x1000
	s_addc_u32 s11, s11, 0
	global_load_dwordx4 v[140:143], v225, s[2:3]
	global_load_dwordx2 v[232:233], v226, s[10:11]
	s_add_u32 s2, s2, 0x2000
	s_addc_u32 s3, s3, 0
	s_add_u32 s10, s10, 0x1000
	s_addc_u32 s11, s11, 0
	global_load_dwordx4 v[144:147], v225, s[4:5]
	s_add_u32 s4, s4, 0x2000
	s_addc_u32 s5, s5, 0
	global_load_dwordx4 v[152:155], v225, s[2:3]
	global_load_dwordx2 v[160:161], v226, s[10:11]
	s_add_u32 s2, s2, 0x2000
	s_addc_u32 s3, s3, 0
	s_add_u32 s10, s10, 0x1000
	s_addc_u32 s11, s11, 0
	global_load_dwordx4 v[156:159], v225, s[4:5]
	s_add_u32 s4, s4, 0x2000
	s_addc_u32 s5, s5, 0
	s_mov_b32 s52, 0x3000
	s_mov_b32 s53, 0x6000
	s_mov_b32 s54, 0
	v_mov_b64_e32 v[0:1], 0
	v_mov_b64_e32 v[2:3], 0
	v_mov_b64_e32 v[4:5], 0
	v_mov_b64_e32 v[6:7], 0
	v_mov_b64_e32 v[8:9], 0
	v_mov_b64_e32 v[10:11], 0
	v_mov_b64_e32 v[12:13], 0
	v_mov_b64_e32 v[14:15], 0
	v_mov_b64_e32 v[16:17], 0
	v_mov_b64_e32 v[18:19], 0
	v_mov_b64_e32 v[20:21], 0
	v_mov_b64_e32 v[22:23], 0
	v_mov_b64_e32 v[24:25], 0
	v_mov_b64_e32 v[26:27], 0
	v_mov_b64_e32 v[28:29], 0
	v_mov_b64_e32 v[30:31], 0
	v_mov_b32_e32 v162, 0xf149f2ca
	v_mov_b32_e32 v164, 0xf149f2ca
	v_mov_b32_e32 v163, 0x7149f2ca
	v_mov_b32_e32 v165, 0
	s_barrier
	s_waitcnt vmcnt(7)
	ds_write_b128 v218, v[136:139]
	s_waitcnt vmcnt(6)
	ds_write_b64 v219, v[230:231]
	s_waitcnt vmcnt(5)
	ds_write_b128 v218, v[140:143] offset:13312
	s_waitcnt vmcnt(4)
	ds_write_b64 v219, v[232:233] offset:13312
	s_waitcnt vmcnt(3)
	ds_write_b128 v221, v[144:147]
	s_waitcnt lgkmcnt(0)
	s_barrier
	s_cmp_eq_u32 s58, 0
	s_cbranch_scc1 .Lamla_prio
	s_setprio 1
.Lamla_prio:
	ds_read_b128 v[136:139], v229 offset:0
	ds_read_b128 v[140:143], v229 offset:6656
	ds_read_b128 v[144:147], v229 offset:32
	ds_read_b128 v[148:151], v229 offset:6688
	s_waitcnt lgkmcnt(3)
	v_mfma_f32_32x32x16_bf16 v[32:47], v[136:139], v[112:115], 0
	ds_read_b128 v[136:139], v229 offset:64
	s_waitcnt lgkmcnt(3)
	v_mfma_f32_32x32x16_bf16 v[48:63], v[140:143], v[112:115], 0
	ds_read_b128 v[140:143], v229 offset:6720
	s_waitcnt lgkmcnt(3)
	v_mfma_f32_32x32x16_bf16 v[32:47], v[144:147], v[116:119], v[32:47]
	ds_read_b128 v[144:147], v229 offset:96
	s_waitcnt lgkmcnt(3)
	v_mfma_f32_32x32x16_bf16 v[48:63], v[148:151], v[116:119], v[48:63]
	ds_read_b128 v[148:151], v229 offset:6752
	s_waitcnt lgkmcnt(3)
	v_mfma_f32_32x32x16_bf16 v[32:47], v[136:139], v[120:123], v[32:47]
	ds_read_b128 v[136:139], v229 offset:128
	s_waitcnt lgkmcnt(3)
	v_mfma_f32_32x32x16_bf16 v[48:63], v[140:143], v[120:123], v[48:63]
	ds_read_b128 v[140:143], v229 offset:6784
	s_waitcnt lgkmcnt(3)
	v_mfma_f32_32x32x16_bf16 v[32:47], v[144:147], v[124:127], v[32:47]
	ds_read_b128 v[144:147], v229 offset:160
	s_waitcnt lgkmcnt(3)
	v_mfma_f32_32x32x16_bf16 v[48:63], v[148:151], v[124:127], v[48:63]
	ds_read_b128 v[148:151], v229 offset:6816
	s_waitcnt lgkmcnt(3)
	v_mfma_f32_32x32x16_bf16 v[32:47], v[136:139], v[128:131], v[32:47]
	s_waitcnt lgkmcnt(2)
	v_mfma_f32_32x32x16_bf16 v[48:63], v[140:143], v[128:131], v[48:63]
	s_waitcnt lgkmcnt(1)
	v_mfma_f32_32x32x16_bf16 v[32:47], v[144:147], v[132:135], v[32:47]
	s_waitcnt lgkmcnt(0)
	v_mfma_f32_32x32x16_bf16 v[48:63], v[148:151], v[132:135], v[48:63]
	s_waitcnt lgkmcnt(0)
	s_barrier
	s_mov_b32 s55, s52
	s_mov_b32 s52, s53
	s_mov_b32 s53, s54
	s_mov_b32 s54, s55
	s_mov_b32 s9, 0
	global_load_dwordx4 v[208:211], v225, s[2:3]
	global_load_dwordx2 v[216:217], v226, s[10:11]
	global_load_dwordx4 v[212:215], v225, s[4:5]
	s_add_u32 s2, s2, 0x2000
	s_addc_u32 s3, s3, 0
	s_add_u32 s10, s10, 0x1000
	s_addc_u32 s11, s11, 0
	s_add_u32 s4, s4, 0x2000
	s_addc_u32 s5, s5, 0
	ds_read_b128 v[136:139], v229 offset:13312
	ds_read_b128 v[140:143], v229 offset:19968
	ds_read_b128 v[144:147], v229 offset:13344
	ds_read_b128 v[148:151], v229 offset:20000
	s_waitcnt lgkmcnt(3)
	v_mfma_f32_32x32x16_bf16 v[64:79], v[136:139], v[112:115], 0
	v_add_u32_e32 v223, s53, v220
	v_add_u32_e32 v224, s54, v221
	v_max3_f32 v168, v32, v33, v34
	v_max3_f32 v170, v48, v49, v50
	v_max3_f32 v168, v168, v35, v36
	v_max3_f32 v170, v170, v51, v52
	v_max3_f32 v168, v168, v37, v38
	ds_read_b128 v[136:139], v229 offset:13376
	s_waitcnt lgkmcnt(3)
	v_mfma_f32_32x32x16_bf16 v[80:95], v[140:143], v[112:115], 0
	v_max3_f32 v170, v170, v53, v54
	v_max3_f32 v168, v168, v39, v40
	v_max3_f32 v170, v170, v55, v56
	v_max3_f32 v168, v168, v41, v42
	v_max3_f32 v170, v170, v57, v58
	v_max3_f32 v168, v168, v43, v44
	v_max3_f32 v170, v170, v59, v60
	v_max3_f32 v168, v168, v45, v46
	v_max3_f32 v170, v170, v61, v62
	v_max_f32_e32 v168, v168, v47
	ds_read_b128 v[140:143], v229 offset:20032
	s_waitcnt lgkmcnt(3)
	v_mfma_f32_32x32x16_bf16 v[64:79], v[144:147], v[116:119], v[64:79]
	v_max_f32_e32 v170, v170, v63
	v_max_f32_e32 v168, v168, v170
	v_mov_b32_e32 v170, v168
	s_nop 1
	v_permlane32_swap_b32_e32 v168, v170
	v_max_f32_e32 v168, v168, v170
	v_mul_f32_e32 v168, 0x3e16c740, v168
	v_cmp_gt_f32_e32 vcc, v168, v164
	s_cbranch_vccz .Lamla_nors_1
	v_max_f32_e32 v170, v162, v168
	v_sub_f32_e32 v166, v162, v170
	v_exp_f32_e32 v166, v166
	v_mov_b32_e32 v162, v170
	v_add_f32_e32 v164, 0x41000000, v170
	v_xor_b32_e32 v163, 0x80000000, v170
	v_mul_f32_e32 v165, v165, v166
	s_mov_b32 s9, 1
.Lamla_nors_1:
	v_fmamk_f32 v32, v32, 0x3e16c740, v163
	v_fmamk_f32 v48, v48, 0x3e16c740, v163
	v_exp_f32_e32 v32, v32
	v_exp_f32_e32 v48, v48
	v_fmamk_f32 v33, v33, 0x3e16c740, v163
	ds_read_b128 v[144:147], v229 offset:13408
	s_waitcnt lgkmcnt(3)
	v_mfma_f32_32x32x16_bf16 v[80:95], v[148:151], v[116:119], v[80:95]
	v_fmamk_f32 v49, v49, 0x3e16c740, v163
	v_exp_f32_e32 v33, v33
	v_exp_f32_e32 v49, v49
	v_fmamk_f32 v34, v34, 0x3e16c740, v163
	v_fmamk_f32 v50, v50, 0x3e16c740, v163
	v_exp_f32_e32 v34, v34
	v_exp_f32_e32 v50, v50
	v_add_f32_e32 v171, v32, v33
	v_add_f32_e32 v172, v48, v49
	v_cvt_pk_bf16_f32 v96, v32, v33
	v_cvt_pk_bf16_f32 v104, v48, v49
	v_fmamk_f32 v35, v35, 0x3e16c740, v163
	ds_read_b128 v[148:151], v229 offset:20064
	s_waitcnt lgkmcnt(3)
	v_mfma_f32_32x32x16_bf16 v[64:79], v[136:139], v[120:123], v[64:79]
	v_fmamk_f32 v51, v51, 0x3e16c740, v163
	v_exp_f32_e32 v35, v35
	v_exp_f32_e32 v51, v51
	v_fmamk_f32 v36, v36, 0x3e16c740, v163
	v_fmamk_f32 v52, v52, 0x3e16c740, v163
	v_exp_f32_e32 v36, v36
	v_exp_f32_e32 v52, v52
	v_add_f32_e32 v171, v171, v34
	v_add_f32_e32 v172, v172, v50
	v_add_f32_e32 v171, v171, v35
	v_add_f32_e32 v172, v172, v51
	ds_read_b128 v[136:139], v229 offset:13440
	s_waitcnt lgkmcnt(3)
	v_mfma_f32_32x32x16_bf16 v[80:95], v[140:143], v[120:123], v[80:95]
	v_cvt_pk_bf16_f32 v97, v34, v35
	v_cvt_pk_bf16_f32 v105, v50, v51
	v_fmamk_f32 v37, v37, 0x3e16c740, v163
	v_fmamk_f32 v53, v53, 0x3e16c740, v163
	v_exp_f32_e32 v37, v37
	v_exp_f32_e32 v53, v53
	v_fmamk_f32 v38, v38, 0x3e16c740, v163
	v_fmamk_f32 v54, v54, 0x3e16c740, v163
	v_exp_f32_e32 v38, v38
	v_exp_f32_e32 v54, v54
	v_add_f32_e32 v171, v171, v36
	ds_read_b128 v[140:143], v229 offset:20096
	s_waitcnt lgkmcnt(3)
	v_mfma_f32_32x32x16_bf16 v[64:79], v[144:147], v[124:127], v[64:79]
	v_add_f32_e32 v172, v172, v52
	v_add_f32_e32 v171, v171, v37
	v_add_f32_e32 v172, v172, v53
	v_cvt_pk_bf16_f32 v98, v36, v37
	v_cvt_pk_bf16_f32 v106, v52, v53
	v_fmamk_f32 v39, v39, 0x3e16c740, v163
	v_fmamk_f32 v55, v55, 0x3e16c740, v163
	v_exp_f32_e32 v39, v39
	v_exp_f32_e32 v55, v55
	v_fmamk_f32 v40, v40, 0x3e16c740, v163
	v_fmamk_f32 v56, v56, 0x3e16c740, v163
	v_exp_f32_e32 v40, v40
	ds_read_b128 v[144:147], v229 offset:13472
	s_waitcnt vmcnt(5)
	ds_write_b128 v218, v[152:155]
	s_waitcnt vmcnt(4)
	ds_write_b64 v219, v[160:161]
	s_waitcnt vmcnt(3)
	ds_write_b128 v224, v[156:159]
	s_waitcnt lgkmcnt(6)
	v_mfma_f32_32x32x16_bf16 v[80:95], v[148:151], v[124:127], v[80:95]
	v_exp_f32_e32 v56, v56
	v_add_f32_e32 v171, v171, v38
	v_add_f32_e32 v172, v172, v54
	v_add_f32_e32 v171, v171, v39
	v_add_f32_e32 v172, v172, v55
	v_cvt_pk_bf16_f32 v99, v38, v39
	v_cvt_pk_bf16_f32 v107, v54, v55
	v_fmamk_f32 v41, v41, 0x3e16c740, v163
	v_fmamk_f32 v57, v57, 0x3e16c740, v163
	v_exp_f32_e32 v41, v41
	v_exp_f32_e32 v57, v57
	v_fmamk_f32 v42, v42, 0x3e16c740, v163
	v_fmamk_f32 v58, v58, 0x3e16c740, v163
	ds_read_b128 v[148:151], v229 offset:20128
	s_waitcnt lgkmcnt(6)
	v_mfma_f32_32x32x16_bf16 v[64:79], v[136:139], v[128:131], v[64:79]
	v_exp_f32_e32 v42, v42
	v_exp_f32_e32 v58, v58
	v_add_f32_e32 v171, v171, v40
	v_add_f32_e32 v172, v172, v56
	v_add_f32_e32 v171, v171, v41
	v_add_f32_e32 v172, v172, v57
	v_cvt_pk_bf16_f32 v100, v40, v41
	v_cvt_pk_bf16_f32 v108, v56, v57
	v_fmamk_f32 v43, v43, 0x3e16c740, v163
	v_fmamk_f32 v59, v59, 0x3e16c740, v163
	v_exp_f32_e32 v43, v43
	v_exp_f32_e32 v59, v59
	ds_read_b64_tr_b16 v[176:177], v223 offset:0
	ds_read_b64_tr_b16 v[178:179], v223 offset:1536
	ds_read_b64_tr_b16 v[180:181], v223 offset:64
	ds_read_b64_tr_b16 v[182:183], v223 offset:1600
	s_waitcnt lgkmcnt(9)
	v_mfma_f32_32x32x16_bf16 v[80:95], v[140:143], v[128:131], v[80:95]
	v_fmamk_f32 v44, v44, 0x3e16c740, v163
	v_fmamk_f32 v60, v60, 0x3e16c740, v163
	v_exp_f32_e32 v44, v44
	v_exp_f32_e32 v60, v60
	v_add_f32_e32 v171, v171, v42
	v_add_f32_e32 v172, v172, v58
	v_add_f32_e32 v171, v171, v43
	v_add_f32_e32 v172, v172, v59
	v_cvt_pk_bf16_f32 v101, v42, v43
	v_cvt_pk_bf16_f32 v109, v58, v59
	v_fmamk_f32 v45, v45, 0x3e16c740, v163
	v_fmamk_f32 v61, v61, 0x3e16c740, v163
	s_waitcnt lgkmcnt(8)
	v_mfma_f32_32x32x16_bf16 v[64:79], v[144:147], v[132:135], v[64:79]
	v_exp_f32_e32 v45, v45
	v_exp_f32_e32 v61, v61
	v_fmamk_f32 v46, v46, 0x3e16c740, v163
	v_fmamk_f32 v62, v62, 0x3e16c740, v163
	v_exp_f32_e32 v46, v46
	v_exp_f32_e32 v62, v62
	v_add_f32_e32 v171, v171, v44
	v_add_f32_e32 v172, v172, v60
	v_add_f32_e32 v171, v171, v45
	v_add_f32_e32 v172, v172, v61
	v_cvt_pk_bf16_f32 v102, v44, v45
	s_waitcnt lgkmcnt(4)
	v_mfma_f32_32x32x16_bf16 v[80:95], v[148:151], v[132:135], v[80:95]
	v_cvt_pk_bf16_f32 v110, v60, v61
	v_fmamk_f32 v47, v47, 0x3e16c740, v163
	v_fmamk_f32 v63, v63, 0x3e16c740, v163
	v_exp_f32_e32 v47, v47
	v_exp_f32_e32 v63, v63
	v_add_f32_e32 v171, v171, v46
	v_add_f32_e32 v172, v172, v62
	v_add_f32_e32 v171, v171, v47
	v_add_f32_e32 v172, v172, v63
	v_cvt_pk_bf16_f32 v103, v46, v47
	v_cvt_pk_bf16_f32 v111, v62, v63
	v_add_f32_e32 v165, v165, v171
	v_add_f32_e32 v165, v165, v172
	s_waitcnt lgkmcnt(0)
	s_barrier
	s_cmp_eq_u32 s7, 0
	s_cbranch_scc1 .Lamla_tail
.Lamla_loop:
	s_mov_b32 s55, s52
	s_mov_b32 s52, s53
	s_mov_b32 s53, s54
	s_mov_b32 s54, s55
	s_mov_b32 s9, 0
	global_load_dwordx4 v[152:155], v225, s[2:3]
	global_load_dwordx2 v[160:161], v226, s[10:11]
	global_load_dwordx4 v[156:159], v225, s[4:5]
	s_add_u32 s2, s2, 0x2000
	s_addc_u32 s3, s3, 0
	s_add_u32 s10, s10, 0x1000
	s_addc_u32 s11, s11, 0
	s_add_u32 s4, s4, 0x2000
	s_addc_u32 s5, s5, 0
	ds_read_b128 v[136:139], v229 offset:0
	ds_read_b128 v[140:143], v229 offset:6656
	ds_read_b128 v[144:147], v229 offset:32
	ds_read_b128 v[148:151], v229 offset:6688
	v_mfma_f32_32x32x16_bf16 v[0:15], v[176:179], v[96:99], v[0:15]
	v_add_u32_e32 v222, s53, v220
	v_add_u32_e32 v224, s54, v221
	v_max3_f32 v168, v64, v65, v66
	v_max3_f32 v170, v80, v81, v82
	ds_read_b64_tr_b16 v[184:185], v223 offset:6144
	ds_read_b64_tr_b16 v[186:187], v223 offset:7680
	ds_read_b64_tr_b16 v[188:189], v223 offset:6208
	ds_read_b64_tr_b16 v[190:191], v223 offset:7744
	v_mfma_f32_32x32x16_bf16 v[16:31], v[180:183], v[96:99], v[16:31]
	v_max3_f32 v168, v168, v67, v68
	v_max3_f32 v170, v170, v83, v84
	v_max3_f32 v168, v168, v69, v70
	v_max3_f32 v170, v170, v85, v86
	v_max3_f32 v168, v168, v71, v72
	v_max3_f32 v170, v170, v87, v88
	ds_read_b64_tr_b16 v[192:193], v223 offset:3072
	ds_read_b64_tr_b16 v[194:195], v223 offset:4608
	ds_read_b64_tr_b16 v[196:197], v223 offset:3136
	ds_read_b64_tr_b16 v[198:199], v223 offset:4672
	s_waitcnt lgkmcnt(11)
	v_mfma_f32_32x32x16_bf16 v[32:47], v[136:139], v[112:115], 0
	v_max3_f32 v168, v168, v73, v74
	v_max3_f32 v170, v170, v89, v90
	v_max3_f32 v168, v168, v75, v76
	v_max3_f32 v170, v170, v91, v92
	v_max3_f32 v168, v168, v77, v78
	v_max3_f32 v170, v170, v93, v94
	v_max_f32_e32 v168, v168, v79
	v_max_f32_e32 v170, v170, v95
	v_max_f32_e32 v168, v168, v170
	ds_read_b128 v[136:139], v229 offset:64
	ds_read_b64_tr_b16 v[200:201], v223 offset:9216
	ds_read_b64_tr_b16 v[202:203], v223 offset:10752
	ds_read_b64_tr_b16 v[204:205], v223 offset:9280
	ds_read_b64_tr_b16 v[206:207], v223 offset:10816
	s_waitcnt lgkmcnt(15)
	v_mfma_f32_32x32x16_bf16 v[48:63], v[140:143], v[112:115], 0
	v_mov_b32_e32 v170, v168
	s_nop 1
	v_permlane32_swap_b32_e32 v168, v170
	v_max_f32_e32 v168, v168, v170
	v_mul_f32_e32 v168, 0x3e16c740, v168
	v_cmp_gt_f32_e32 vcc, v168, v164
	s_cbranch_vccz .Lamla_nors_2
	v_max_f32_e32 v170, v162, v168
	v_sub_f32_e32 v166, v162, v170
	v_exp_f32_e32 v166, v166
	v_mov_b32_e32 v162, v170
	v_add_f32_e32 v164, 0x41000000, v170
	v_xor_b32_e32 v163, 0x80000000, v170
	v_mul_f32_e32 v165, v165, v166
	s_mov_b32 s9, 1
.Lamla_nors_2:
	v_fmamk_f32 v64, v64, 0x3e16c740, v163
	v_fmamk_f32 v80, v80, 0x3e16c740, v163
	v_exp_f32_e32 v64, v64
	ds_read_b128 v[140:143], v229 offset:6720
	s_waitcnt lgkmcnt(15)
	v_mfma_f32_32x32x16_bf16 v[32:47], v[144:147], v[116:119], v[32:47]
	v_exp_f32_e32 v80, v80
	v_fmamk_f32 v65, v65, 0x3e16c740, v163
	v_fmamk_f32 v81, v81, 0x3e16c740, v163
	v_exp_f32_e32 v65, v65
	v_exp_f32_e32 v81, v81
	ds_read_b128 v[144:147], v229 offset:96
	s_waitcnt lgkmcnt(15)
	v_mfma_f32_32x32x16_bf16 v[48:63], v[148:151], v[116:119], v[48:63]
	v_fmamk_f32 v66, v66, 0x3e16c740, v163
	v_fmamk_f32 v82, v82, 0x3e16c740, v163
	v_exp_f32_e32 v66, v66
	v_exp_f32_e32 v82, v82
	v_add_f32_e32 v171, v64, v65
	v_add_f32_e32 v172, v80, v81
	v_cvt_pk_bf16_f32 v96, v64, v65
	ds_read_b128 v[148:151], v229 offset:6752
	s_waitcnt lgkmcnt(7)
	v_mfma_f32_32x32x16_bf16 v[32:47], v[136:139], v[120:123], v[32:47]
	v_fmamk_f32 v67, v67, 0x3e16c740, v163
	v_fmamk_f32 v83, v83, 0x3e16c740, v163
	v_exp_f32_e32 v67, v67
	v_exp_f32_e32 v83, v83
	v_fmamk_f32 v68, v68, 0x3e16c740, v163
	v_fmamk_f32 v84, v84, 0x3e16c740, v163
	ds_read_b128 v[136:139], v229 offset:128
	s_waitcnt lgkmcnt(3)
	v_mfma_f32_32x32x16_bf16 v[48:63], v[140:143], v[120:123], v[48:63]
	v_exp_f32_e32 v68, v68
	v_exp_f32_e32 v84, v84
	v_add_f32_e32 v171, v171, v66
	v_add_f32_e32 v172, v172, v82
	v_add_f32_e32 v171, v171, v67
	v_add_f32_e32 v172, v172, v83
	v_cvt_pk_bf16_f32 v97, v66, v67
	ds_read_b128 v[140:143], v229 offset:6784
	s_waitcnt lgkmcnt(3)
	v_mfma_f32_32x32x16_bf16 v[32:47], v[144:147], v[124:127], v[32:47]
	v_fmamk_f32 v69, v69, 0x3e16c740, v163
	v_fmamk_f32 v85, v85, 0x3e16c740, v163
	v_exp_f32_e32 v69, v69
	v_exp_f32_e32 v85, v85
	v_fmamk_f32 v70, v70, 0x3e16c740, v163
	v_fmamk_f32 v86, v86, 0x3e16c740, v163
	v_exp_f32_e32 v70, v70
	ds_read_b128 v[144:147], v229 offset:160
	s_waitcnt lgkmcnt(3)
	v_mfma_f32_32x32x16_bf16 v[48:63], v[148:151], v[124:127], v[48:63]
	v_exp_f32_e32 v86, v86
	v_add_f32_e32 v171, v171, v68
	v_add_f32_e32 v172, v172, v84
	v_add_f32_e32 v171, v171, v69
	v_add_f32_e32 v172, v172, v85
	v_cvt_pk_bf16_f32 v98, v68, v69
	v_fmamk_f32 v71, v71, 0x3e16c740, v163
	ds_read_b128 v[148:151], v229 offset:6816
	s_waitcnt lgkmcnt(3)
	v_mfma_f32_32x32x16_bf16 v[32:47], v[136:139], v[128:131], v[32:47]
	v_fmamk_f32 v87, v87, 0x3e16c740, v163
	v_exp_f32_e32 v71, v71
	v_exp_f32_e32 v87, v87
	v_fmamk_f32 v72, v72, 0x3e16c740, v163
	v_fmamk_f32 v88, v88, 0x3e16c740, v163
	v_exp_f32_e32 v72, v72
	s_waitcnt lgkmcnt(2)
	v_mfma_f32_32x32x16_bf16 v[48:63], v[140:143], v[128:131], v[48:63]
	v_exp_f32_e32 v88, v88
	v_add_f32_e32 v171, v171, v70
	v_add_f32_e32 v172, v172, v86
	v_add_f32_e32 v171, v171, v71
	v_add_f32_e32 v172, v172, v87
	v_cvt_pk_bf16_f32 v99, v70, v71
	v_fmamk_f32 v73, v73, 0x3e16c740, v163
	v_fmamk_f32 v89, v89, 0x3e16c740, v163
	s_waitcnt vmcnt(5)
	ds_write_b128 v218, v[208:211] offset:13312
	s_waitcnt vmcnt(4)
	ds_write_b64 v219, v[216:217] offset:13312
	s_waitcnt vmcnt(3)
	ds_write_b128 v224, v[212:215]
	s_waitcnt lgkmcnt(4)
	v_mfma_f32_32x32x16_bf16 v[32:47], v[144:147], v[132:135], v[32:47]
	v_exp_f32_e32 v73, v73
	v_exp_f32_e32 v89, v89
	v_fmamk_f32 v74, v74, 0x3e16c740, v163
	v_fmamk_f32 v90, v90, 0x3e16c740, v163
	v_exp_f32_e32 v74, v74
	v_exp_f32_e32 v90, v90
	s_waitcnt lgkmcnt(3)
	v_mfma_f32_32x32x16_bf16 v[48:63], v[148:151], v[132:135], v[48:63]
	v_add_f32_e32 v171, v171, v72
	v_add_f32_e32 v172, v172, v88
	v_add_f32_e32 v171, v171, v73
	v_add_f32_e32 v172, v172, v89
	v_fmamk_f32 v75, v75, 0x3e16c740, v163
	v_fmamk_f32 v91, v91, 0x3e16c740, v163
	v_exp_f32_e32 v75, v75
	v_mfma_f32_32x32x16_bf16 v[0:15], v[184:187], v[104:107], v[0:15]
	v_exp_f32_e32 v91, v91
	v_fmamk_f32 v76, v76, 0x3e16c740, v163
	v_fmamk_f32 v92, v92, 0x3e16c740, v163
	v_exp_f32_e32 v76, v76
	v_exp_f32_e32 v92, v92
	ds_read_b64_tr_b16 v[176:177], v222 offset:0
	ds_read_b64_tr_b16 v[178:179], v222 offset:1536
	ds_read_b64_tr_b16 v[180:181], v222 offset:64
	ds_read_b64_tr_b16 v[182:183], v222 offset:1600
	v_mfma_f32_32x32x16_bf16 v[16:31], v[188:191], v[104:107], v[16:31]
	v_cvt_pk_bf16_f32 v104, v80, v81
	v_cvt_pk_bf16_f32 v105, v82, v83
	v_cvt_pk_bf16_f32 v106, v84, v85
	v_cvt_pk_bf16_f32 v107, v86, v87
	v_add_f32_e32 v171, v171, v74
	v_add_f32_e32 v172, v172, v90
	v_add_f32_e32 v171, v171, v75
	v_add_f32_e32 v172, v172, v91
	v_fmamk_f32 v77, v77, 0x3e16c740, v163
	v_fmamk_f32 v93, v93, 0x3e16c740, v163
	v_exp_f32_e32 v77, v77
	v_exp_f32_e32 v93, v93
	v_mfma_f32_32x32x16_bf16 v[0:15], v[192:195], v[100:103], v[0:15]
	v_fmamk_f32 v78, v78, 0x3e16c740, v163
	v_fmamk_f32 v94, v94, 0x3e16c740, v163
	v_exp_f32_e32 v78, v78
	v_exp_f32_e32 v94, v94
	v_add_f32_e32 v171, v171, v76
	v_add_f32_e32 v172, v172, v92
	v_mfma_f32_32x32x16_bf16 v[16:31], v[196:199], v[100:103], v[16:31]
	v_cvt_pk_bf16_f32 v100, v72, v73
	v_cvt_pk_bf16_f32 v101, v74, v75
	v_add_f32_e32 v171, v171, v77
	v_add_f32_e32 v172, v172, v93
	v_cvt_pk_bf16_f32 v102, v76, v77
	v_fmamk_f32 v79, v79, 0x3e16c740, v163
	v_fmamk_f32 v95, v95, 0x3e16c740, v163
	v_exp_f32_e32 v79, v79
	v_exp_f32_e32 v95, v95
	v_mfma_f32_32x32x16_bf16 v[0:15], v[200:203], v[108:111], v[0:15]
	v_add_f32_e32 v171, v171, v78
	v_add_f32_e32 v172, v172, v94
	v_add_f32_e32 v171, v171, v79
	v_add_f32_e32 v172, v172, v95
	v_cvt_pk_bf16_f32 v103, v78, v79
	v_add_f32_e32 v165, v165, v171
	v_add_f32_e32 v165, v165, v172
	v_mfma_f32_32x32x16_bf16 v[16:31], v[204:207], v[108:111], v[16:31]
	v_cvt_pk_bf16_f32 v108, v88, v89
	v_cvt_pk_bf16_f32 v109, v90, v91
	v_cvt_pk_bf16_f32 v110, v92, v93
	v_cvt_pk_bf16_f32 v111, v94, v95
	s_cmp_lg_u32 s9, 0
	s_cbranch_scc0 .Lamla_noresc_3
	s_nop 15
	v_pk_mul_f32 v[0:1], v[0:1], v[166:167] op_sel_hi:[1,0]
	v_pk_mul_f32 v[2:3], v[2:3], v[166:167] op_sel_hi:[1,0]
	v_pk_mul_f32 v[4:5], v[4:5], v[166:167] op_sel_hi:[1,0]
	v_pk_mul_f32 v[6:7], v[6:7], v[166:167] op_sel_hi:[1,0]
	v_pk_mul_f32 v[8:9], v[8:9], v[166:167] op_sel_hi:[1,0]
	v_pk_mul_f32 v[10:11], v[10:11], v[166:167] op_sel_hi:[1,0]
	v_pk_mul_f32 v[12:13], v[12:13], v[166:167] op_sel_hi:[1,0]
	v_pk_mul_f32 v[14:15], v[14:15], v[166:167] op_sel_hi:[1,0]
	v_pk_mul_f32 v[16:17], v[16:17], v[166:167] op_sel_hi:[1,0]
	v_pk_mul_f32 v[18:19], v[18:19], v[166:167] op_sel_hi:[1,0]
	v_pk_mul_f32 v[20:21], v[20:21], v[166:167] op_sel_hi:[1,0]
	v_pk_mul_f32 v[22:23], v[22:23], v[166:167] op_sel_hi:[1,0]
	v_pk_mul_f32 v[24:25], v[24:25], v[166:167] op_sel_hi:[1,0]
	v_pk_mul_f32 v[26:27], v[26:27], v[166:167] op_sel_hi:[1,0]
	v_pk_mul_f32 v[28:29], v[28:29], v[166:167] op_sel_hi:[1,0]
	v_pk_mul_f32 v[30:31], v[30:31], v[166:167] op_sel_hi:[1,0]
.Lamla_noresc_3:
	s_waitcnt lgkmcnt(0)
	s_barrier
	s_mov_b32 s55, s52
	s_mov_b32 s52, s53
	s_mov_b32 s53, s54
	s_mov_b32 s54, s55
	s_mov_b32 s9, 0
	global_load_dwordx4 v[208:211], v225, s[2:3]
	global_load_dwordx2 v[216:217], v226, s[10:11]
	global_load_dwordx4 v[212:215], v225, s[4:5]
	s_add_u32 s2, s2, 0x2000
	s_addc_u32 s3, s3, 0
	s_add_u32 s10, s10, 0x1000
	s_addc_u32 s11, s11, 0
	s_add_u32 s4, s4, 0x2000
	s_addc_u32 s5, s5, 0
	ds_read_b128 v[136:139], v229 offset:13312
	ds_read_b128 v[140:143], v229 offset:19968
	ds_read_b128 v[144:147], v229 offset:13344
	ds_read_b128 v[148:151], v229 offset:20000
	v_mfma_f32_32x32x16_bf16 v[0:15], v[176:179], v[96:99], v[0:15]
	v_add_u32_e32 v223, s53, v220
	v_add_u32_e32 v224, s54, v221
	v_max3_f32 v168, v32, v33, v34
	v_max3_f32 v170, v48, v49, v50
	ds_read_b64_tr_b16 v[184:185], v222 offset:6144
	ds_read_b64_tr_b16 v[186:187], v222 offset:7680
	ds_read_b64_tr_b16 v[188:189], v222 offset:6208
	ds_read_b64_tr_b16 v[190:191], v222 offset:7744
	v_mfma_f32_32x32x16_bf16 v[16:31], v[180:183], v[96:99], v[16:31]
	v_max3_f32 v168, v168, v35, v36
	v_max3_f32 v170, v170, v51, v52
	v_max3_f32 v168, v168, v37, v38
	v_max3_f32 v170, v170, v53, v54
	v_max3_f32 v168, v168, v39, v40
	v_max3_f32 v170, v170, v55, v56
	ds_read_b64_tr_b16 v[192:193], v222 offset:3072
	ds_read_b64_tr_b16 v[194:195], v222 offset:4608
	ds_read_b64_tr_b16 v[196:197], v222 offset:3136
	ds_read_b64_tr_b16 v[198:199], v222 offset:4672
	s_waitcnt lgkmcnt(11)
	v_mfma_f32_32x32x16_bf16 v[64:79], v[136:139], v[112:115], 0
	v_max3_f32 v168, v168, v41, v42
	v_max3_f32 v170, v170, v57, v58
	v_max3_f32 v168, v168, v43, v44
	v_max3_f32 v170, v170, v59, v60
	v_max3_f32 v168, v168, v45, v46
	v_max3_f32 v170, v170, v61, v62
	v_max_f32_e32 v168, v168, v47
	v_max_f32_e32 v170, v170, v63
	v_max_f32_e32 v168, v168, v170
	ds_read_b128 v[136:139], v229 offset:13376
	ds_read_b64_tr_b16 v[200:201], v222 offset:9216
	ds_read_b64_tr_b16 v[202:203], v222 offset:10752
	ds_read_b64_tr_b16 v[204:205], v222 offset:9280
	ds_read_b64_tr_b16 v[206:207], v222 offset:10816
	s_waitcnt lgkmcnt(15)
	v_mfma_f32_32x32x16_bf16 v[80:95], v[140:143], v[112:115], 0
	v_mov_b32_e32 v170, v168
	s_nop 1
	v_permlane32_swap_b32_e32 v168, v170
	v_max_f32_e32 v168, v168, v170
	v_mul_f32_e32 v168, 0x3e16c740, v168
	v_cmp_gt_f32_e32 vcc, v168, v164
	s_cbranch_vccz .Lamla_nors_4
	v_max_f32_e32 v170, v162, v168
	v_sub_f32_e32 v166, v162, v170
	v_exp_f32_e32 v166, v166
	v_mov_b32_e32 v162, v170
	v_add_f32_e32 v164, 0x41000000, v170
	v_xor_b32_e32 v163, 0x80000000, v170
	v_mul_f32_e32 v165, v165, v166
	s_mov_b32 s9, 1
.Lamla_nors_4:
	v_fmamk_f32 v32, v32, 0x3e16c740, v163
	v_fmamk_f32 v48, v48, 0x3e16c740, v163
	v_exp_f32_e32 v32, v32
	ds_read_b128 v[140:143], v229 offset:20032
	s_waitcnt lgkmcnt(15)
	v_mfma_f32_32x32x16_bf16 v[64:79], v[144:147], v[116:119], v[64:79]
	v_exp_f32_e32 v48, v48
	v_fmamk_f32 v33, v33, 0x3e16c740, v163
	v_fmamk_f32 v49, v49, 0x3e16c740, v163
	v_exp_f32_e32 v33, v33
	v_exp_f32_e32 v49, v49
	ds_read_b128 v[144:147], v229 offset:13408
	s_waitcnt lgkmcnt(15)
	v_mfma_f32_32x32x16_bf16 v[80:95], v[148:151], v[116:119], v[80:95]
	v_fmamk_f32 v34, v34, 0x3e16c740, v163
	v_fmamk_f32 v50, v50, 0x3e16c740, v163
	v_exp_f32_e32 v34, v34
	v_exp_f32_e32 v50, v50
	v_add_f32_e32 v171, v32, v33
	v_add_f32_e32 v172, v48, v49
	v_cvt_pk_bf16_f32 v96, v32, v33
	ds_read_b128 v[148:151], v229 offset:20064
	s_waitcnt lgkmcnt(7)
	v_mfma_f32_32x32x16_bf16 v[64:79], v[136:139], v[120:123], v[64:79]
	v_fmamk_f32 v35, v35, 0x3e16c740, v163
	v_fmamk_f32 v51, v51, 0x3e16c740, v163
	v_exp_f32_e32 v35, v35
	v_exp_f32_e32 v51, v51
	v_fmamk_f32 v36, v36, 0x3e16c740, v163
	v_fmamk_f32 v52, v52, 0x3e16c740, v163
	ds_read_b128 v[136:139], v229 offset:13440
	s_waitcnt lgkmcnt(3)
	v_mfma_f32_32x32x16_bf16 v[80:95], v[140:143], v[120:123], v[80:95]
	v_exp_f32_e32 v36, v36
	v_exp_f32_e32 v52, v52
	v_add_f32_e32 v171, v171, v34
	v_add_f32_e32 v172, v172, v50
	v_add_f32_e32 v171, v171, v35
	v_add_f32_e32 v172, v172, v51
	v_cvt_pk_bf16_f32 v97, v34, v35
	ds_read_b128 v[140:143], v229 offset:20096
	s_waitcnt lgkmcnt(3)
	v_mfma_f32_32x32x16_bf16 v[64:79], v[144:147], v[124:127], v[64:79]
	v_fmamk_f32 v37, v37, 0x3e16c740, v163
	v_fmamk_f32 v53, v53, 0x3e16c740, v163
	v_exp_f32_e32 v37, v37
	v_exp_f32_e32 v53, v53
	v_fmamk_f32 v38, v38, 0x3e16c740, v163
	v_fmamk_f32 v54, v54, 0x3e16c740, v163
	v_exp_f32_e32 v38, v38
	ds_read_b128 v[144:147], v229 offset:13472
	s_waitcnt lgkmcnt(3)
	v_mfma_f32_32x32x16_bf16 v[80:95], v[148:151], v[124:127], v[80:95]
	v_exp_f32_e32 v54, v54
	v_add_f32_e32 v171, v171, v36
	v_add_f32_e32 v172, v172, v52
	v_add_f32_e32 v171, v171, v37
	v_add_f32_e32 v172, v172, v53
	v_cvt_pk_bf16_f32 v98, v36, v37
	v_fmamk_f32 v39, v39, 0x3e16c740, v163
	ds_read_b128 v[148:151], v229 offset:20128
	s_waitcnt lgkmcnt(3)
	v_mfma_f32_32x32x16_bf16 v[64:79], v[136:139], v[128:131], v[64:79]
	v_fmamk_f32 v55, v55, 0x3e16c740, v163
	v_exp_f32_e32 v39, v39
	v_exp_f32_e32 v55, v55
	v_fmamk_f32 v40, v40, 0x3e16c740, v163
	v_fmamk_f32 v56, v56, 0x3e16c740, v163
	v_exp_f32_e32 v40, v40
	s_waitcnt lgkmcnt(2)
	v_mfma_f32_32x32x16_bf16 v[80:95], v[140:143], v[128:131], v[80:95]
	v_exp_f32_e32 v56, v56
	v_add_f32_e32 v171, v171, v38
	v_add_f32_e32 v172, v172, v54
	v_add_f32_e32 v171, v171, v39
	v_add_f32_e32 v172, v172, v55
	v_cvt_pk_bf16_f32 v99, v38, v39
	v_fmamk_f32 v41, v41, 0x3e16c740, v163
	v_fmamk_f32 v57, v57, 0x3e16c740, v163
	s_waitcnt vmcnt(5)
	ds_write_b128 v218, v[152:155]
	s_waitcnt vmcnt(4)
	ds_write_b64 v219, v[160:161]
	s_waitcnt vmcnt(3)
	ds_write_b128 v224, v[156:159]
	s_waitcnt lgkmcnt(4)
	v_mfma_f32_32x32x16_bf16 v[64:79], v[144:147], v[132:135], v[64:79]
	v_exp_f32_e32 v41, v41
	v_exp_f32_e32 v57, v57
	v_fmamk_f32 v42, v42, 0x3e16c740, v163
	v_fmamk_f32 v58, v58, 0x3e16c740, v163
	v_exp_f32_e32 v42, v42
	v_exp_f32_e32 v58, v58
	s_waitcnt lgkmcnt(3)
	v_mfma_f32_32x32x16_bf16 v[80:95], v[148:151], v[132:135], v[80:95]
	v_add_f32_e32 v171, v171, v40
	v_add_f32_e32 v172, v172, v56
	v_add_f32_e32 v171, v171, v41
	v_add_f32_e32 v172, v172, v57
	v_fmamk_f32 v43, v43, 0x3e16c740, v163
	v_fmamk_f32 v59, v59, 0x3e16c740, v163
	v_exp_f32_e32 v43, v43
	v_mfma_f32_32x32x16_bf16 v[0:15], v[184:187], v[104:107], v[0:15]
	v_exp_f32_e32 v59, v59
	v_fmamk_f32 v44, v44, 0x3e16c740, v163
	v_fmamk_f32 v60, v60, 0x3e16c740, v163
	v_exp_f32_e32 v44, v44
	v_exp_f32_e32 v60, v60
	ds_read_b64_tr_b16 v[176:177], v223 offset:0
	ds_read_b64_tr_b16 v[178:179], v223 offset:1536
	ds_read_b64_tr_b16 v[180:181], v223 offset:64
	ds_read_b64_tr_b16 v[182:183], v223 offset:1600
	v_mfma_f32_32x32x16_bf16 v[16:31], v[188:191], v[104:107], v[16:31]
	v_cvt_pk_bf16_f32 v104, v48, v49
	v_cvt_pk_bf16_f32 v105, v50, v51
	v_cvt_pk_bf16_f32 v106, v52, v53
	v_cvt_pk_bf16_f32 v107, v54, v55
	v_add_f32_e32 v171, v171, v42
	v_add_f32_e32 v172, v172, v58
	v_add_f32_e32 v171, v171, v43
	v_add_f32_e32 v172, v172, v59
	v_fmamk_f32 v45, v45, 0x3e16c740, v163
	v_fmamk_f32 v61, v61, 0x3e16c740, v163
	v_exp_f32_e32 v45, v45
	v_exp_f32_e32 v61, v61
	v_mfma_f32_32x32x16_bf16 v[0:15], v[192:195], v[100:103], v[0:15]
	v_fmamk_f32 v46, v46, 0x3e16c740, v163
	v_fmamk_f32 v62, v62, 0x3e16c740, v163
	v_exp_f32_e32 v46, v46
	v_exp_f32_e32 v62, v62
	v_add_f32_e32 v171, v171, v44
	v_add_f32_e32 v172, v172, v60
	v_mfma_f32_32x32x16_bf16 v[16:31], v[196:199], v[100:103], v[16:31]
	v_cvt_pk_bf16_f32 v100, v40, v41
	v_cvt_pk_bf16_f32 v101, v42, v43
	v_add_f32_e32 v171, v171, v45
	v_add_f32_e32 v172, v172, v61
	v_cvt_pk_bf16_f32 v102, v44, v45
	v_fmamk_f32 v47, v47, 0x3e16c740, v163
	v_fmamk_f32 v63, v63, 0x3e16c740, v163
	v_exp_f32_e32 v47, v47
	v_exp_f32_e32 v63, v63
	v_mfma_f32_32x32x16_bf16 v[0:15], v[200:203], v[108:111], v[0:15]
	v_add_f32_e32 v171, v171, v46
	v_add_f32_e32 v172, v172, v62
	v_add_f32_e32 v171, v171, v47
	v_add_f32_e32 v172, v172, v63
	v_cvt_pk_bf16_f32 v103, v46, v47
	v_add_f32_e32 v165, v165, v171
	v_add_f32_e32 v165, v165, v172
	v_mfma_f32_32x32x16_bf16 v[16:31], v[204:207], v[108:111], v[16:31]
	v_cvt_pk_bf16_f32 v108, v56, v57
	v_cvt_pk_bf16_f32 v109, v58, v59
	v_cvt_pk_bf16_f32 v110, v60, v61
	v_cvt_pk_bf16_f32 v111, v62, v63
	s_cmp_lg_u32 s9, 0
	s_cbranch_scc0 .Lamla_noresc_5
	s_nop 15
	v_pk_mul_f32 v[0:1], v[0:1], v[166:167] op_sel_hi:[1,0]
	v_pk_mul_f32 v[2:3], v[2:3], v[166:167] op_sel_hi:[1,0]
	v_pk_mul_f32 v[4:5], v[4:5], v[166:167] op_sel_hi:[1,0]
	v_pk_mul_f32 v[6:7], v[6:7], v[166:167] op_sel_hi:[1,0]
	v_pk_mul_f32 v[8:9], v[8:9], v[166:167] op_sel_hi:[1,0]
	v_pk_mul_f32 v[10:11], v[10:11], v[166:167] op_sel_hi:[1,0]
	v_pk_mul_f32 v[12:13], v[12:13], v[166:167] op_sel_hi:[1,0]
	v_pk_mul_f32 v[14:15], v[14:15], v[166:167] op_sel_hi:[1,0]
	v_pk_mul_f32 v[16:17], v[16:17], v[166:167] op_sel_hi:[1,0]
	v_pk_mul_f32 v[18:19], v[18:19], v[166:167] op_sel_hi:[1,0]
	v_pk_mul_f32 v[20:21], v[20:21], v[166:167] op_sel_hi:[1,0]
	v_pk_mul_f32 v[22:23], v[22:23], v[166:167] op_sel_hi:[1,0]
	v_pk_mul_f32 v[24:25], v[24:25], v[166:167] op_sel_hi:[1,0]
	v_pk_mul_f32 v[26:27], v[26:27], v[166:167] op_sel_hi:[1,0]
	v_pk_mul_f32 v[28:29], v[28:29], v[166:167] op_sel_hi:[1,0]
	v_pk_mul_f32 v[30:31], v[30:31], v[166:167] op_sel_hi:[1,0]

.Lamla_tail:
	s_mov_b32 s55, s52
	s_mov_b32 s52, s53
	s_mov_b32 s53, s54
	s_mov_b32 s54, s55
	s_mov_b32 s9, 0
	global_load_dwordx4 v[156:159], v225, s[4:5]
	s_add_u32 s4, s4, 0x2000
	s_addc_u32 s5, s5, 0
	ds_read_b128 v[136:139], v229 offset:0
	ds_read_b128 v[140:143], v229 offset:6656
	ds_read_b128 v[144:147], v229 offset:32
	ds_read_b128 v[148:151], v229 offset:6688
	v_mfma_f32_32x32x16_bf16 v[0:15], v[176:179], v[96:99], v[0:15]
	v_add_u32_e32 v222, s53, v220
	v_add_u32_e32 v224, s54, v221
	v_max3_f32 v168, v64, v65, v66
	v_max3_f32 v170, v80, v81, v82
	ds_read_b64_tr_b16 v[184:185], v223 offset:6144
	ds_read_b64_tr_b16 v[186:187], v223 offset:7680
	ds_read_b64_tr_b16 v[188:189], v223 offset:6208
	ds_read_b64_tr_b16 v[190:191], v223 offset:7744
	v_mfma_f32_32x32x16_bf16 v[16:31], v[180:183], v[96:99], v[16:31]
	v_max3_f32 v168, v168, v67, v68
	v_max3_f32 v170, v170, v83, v84
	v_max3_f32 v168, v168, v69, v70
	v_max3_f32 v170, v170, v85, v86
	v_max3_f32 v168, v168, v71, v72
	v_max3_f32 v170, v170, v87, v88
	ds_read_b64_tr_b16 v[192:193], v223 offset:3072
	ds_read_b64_tr_b16 v[194:195], v223 offset:4608
	ds_read_b64_tr_b16 v[196:197], v223 offset:3136
	ds_read_b64_tr_b16 v[198:199], v223 offset:4672
	s_waitcnt lgkmcnt(11)
	v_mfma_f32_32x32x16_bf16 v[32:47], v[136:139], v[112:115], 0
	v_max3_f32 v168, v168, v73, v74
	v_max3_f32 v170, v170, v89, v90
	v_max3_f32 v168, v168, v75, v76
	v_max3_f32 v170, v170, v91, v92
	v_max3_f32 v168, v168, v77, v78
	v_max3_f32 v170, v170, v93, v94
	v_max_f32_e32 v168, v168, v79
	v_max_f32_e32 v170, v170, v95
	v_max_f32_e32 v168, v168, v170
	ds_read_b128 v[136:139], v229 offset:64
	ds_read_b64_tr_b16 v[200:201], v223 offset:9216
	ds_read_b64_tr_b16 v[202:203], v223 offset:10752
	ds_read_b64_tr_b16 v[204:205], v223 offset:9280
	ds_read_b64_tr_b16 v[206:207], v223 offset:10816
	s_waitcnt lgkmcnt(15)
	v_mfma_f32_32x32x16_bf16 v[48:63], v[140:143], v[112:115], 0
	v_mov_b32_e32 v170, v168
	s_nop 1
	v_permlane32_swap_b32_e32 v168, v170
	v_max_f32_e32 v168, v168, v170
	v_mul_f32_e32 v168, 0x3e16c740, v168
	v_cmp_gt_f32_e32 vcc, v168, v164
	s_cbranch_vccz .Lamla_nors_6
	v_max_f32_e32 v170, v162, v168
	v_sub_f32_e32 v166, v162, v170
	v_exp_f32_e32 v166, v166
	v_mov_b32_e32 v162, v170
	v_add_f32_e32 v164, 0x41000000, v170
	v_xor_b32_e32 v163, 0x80000000, v170
	v_mul_f32_e32 v165, v165, v166
	s_mov_b32 s9, 1
.Lamla_nors_6:
	v_fmamk_f32 v64, v64, 0x3e16c740, v163
	v_fmamk_f32 v80, v80, 0x3e16c740, v163
	v_exp_f32_e32 v64, v64
	ds_read_b128 v[140:143], v229 offset:6720
	s_waitcnt lgkmcnt(15)
	v_mfma_f32_32x32x16_bf16 v[32:47], v[144:147], v[116:119], v[32:47]
	v_exp_f32_e32 v80, v80
	v_fmamk_f32 v65, v65, 0x3e16c740, v163
	v_fmamk_f32 v81, v81, 0x3e16c740, v163
	v_exp_f32_e32 v65, v65
	v_exp_f32_e32 v81, v81
	ds_read_b128 v[144:147], v229 offset:96
	s_waitcnt lgkmcnt(15)
	v_mfma_f32_32x32x16_bf16 v[48:63], v[148:151], v[116:119], v[48:63]
	v_fmamk_f32 v66, v66, 0x3e16c740, v163
	v_fmamk_f32 v82, v82, 0x3e16c740, v163
	v_exp_f32_e32 v66, v66
	v_exp_f32_e32 v82, v82
	v_add_f32_e32 v171, v64, v65
	v_add_f32_e32 v172, v80, v81
	v_cvt_pk_bf16_f32 v96, v64, v65
	ds_read_b128 v[148:151], v229 offset:6752
	s_waitcnt lgkmcnt(7)
	v_mfma_f32_32x32x16_bf16 v[32:47], v[136:139], v[120:123], v[32:47]
	v_fmamk_f32 v67, v67, 0x3e16c740, v163
	v_fmamk_f32 v83, v83, 0x3e16c740, v163
	v_exp_f32_e32 v67, v67
	v_exp_f32_e32 v83, v83
	v_fmamk_f32 v68, v68, 0x3e16c740, v163
	v_fmamk_f32 v84, v84, 0x3e16c740, v163
	ds_read_b128 v[136:139], v229 offset:128
	s_waitcnt lgkmcnt(3)
	v_mfma_f32_32x32x16_bf16 v[48:63], v[140:143], v[120:123], v[48:63]
	v_exp_f32_e32 v68, v68
	v_exp_f32_e32 v84, v84
	v_add_f32_e32 v171, v171, v66
	v_add_f32_e32 v172, v172, v82
	v_add_f32_e32 v171, v171, v67
	v_add_f32_e32 v172, v172, v83
	v_cvt_pk_bf16_f32 v97, v66, v67
	ds_read_b128 v[140:143], v229 offset:6784
	s_waitcnt lgkmcnt(3)
	v_mfma_f32_32x32x16_bf16 v[32:47], v[144:147], v[124:127], v[32:47]
	v_fmamk_f32 v69, v69, 0x3e16c740, v163
	v_fmamk_f32 v85, v85, 0x3e16c740, v163
	v_exp_f32_e32 v69, v69
	v_exp_f32_e32 v85, v85
	v_fmamk_f32 v70, v70, 0x3e16c740, v163
	v_fmamk_f32 v86, v86, 0x3e16c740, v163
	v_exp_f32_e32 v70, v70
	ds_read_b128 v[144:147], v229 offset:160
	s_waitcnt lgkmcnt(3)
	v_mfma_f32_32x32x16_bf16 v[48:63], v[148:151], v[124:127], v[48:63]
	v_exp_f32_e32 v86, v86
	v_add_f32_e32 v171, v171, v68
	v_add_f32_e32 v172, v172, v84
	v_add_f32_e32 v171, v171, v69
	v_add_f32_e32 v172, v172, v85
	v_cvt_pk_bf16_f32 v98, v68, v69
	v_fmamk_f32 v71, v71, 0x3e16c740, v163
	ds_read_b128 v[148:151], v229 offset:6816
	s_waitcnt lgkmcnt(3)
	v_mfma_f32_32x32x16_bf16 v[32:47], v[136:139], v[128:131], v[32:47]
	v_fmamk_f32 v87, v87, 0x3e16c740, v163
	v_exp_f32_e32 v71, v71
	v_exp_f32_e32 v87, v87
	v_fmamk_f32 v72, v72, 0x3e16c740, v163
	v_fmamk_f32 v88, v88, 0x3e16c740, v163
	v_exp_f32_e32 v72, v72
	s_waitcnt lgkmcnt(2)
	v_mfma_f32_32x32x16_bf16 v[48:63], v[140:143], v[128:131], v[48:63]
	v_exp_f32_e32 v88, v88
	v_add_f32_e32 v171, v171, v70
	v_add_f32_e32 v172, v172, v86
	v_add_f32_e32 v171, v171, v71
	v_add_f32_e32 v172, v172, v87
	v_cvt_pk_bf16_f32 v99, v70, v71
	v_fmamk_f32 v73, v73, 0x3e16c740, v163
	v_fmamk_f32 v89, v89, 0x3e16c740, v163
	s_waitcnt vmcnt(3)
	ds_write_b128 v218, v[208:211] offset:13312
	s_waitcnt vmcnt(2)
	ds_write_b64 v219, v[216:217] offset:13312
	s_waitcnt vmcnt(1)
	ds_write_b128 v224, v[212:215]
	s_waitcnt lgkmcnt(4)
	v_mfma_f32_32x32x16_bf16 v[32:47], v[144:147], v[132:135], v[32:47]
	v_exp_f32_e32 v73, v73
	v_exp_f32_e32 v89, v89
	v_fmamk_f32 v74, v74, 0x3e16c740, v163
	v_fmamk_f32 v90, v90, 0x3e16c740, v163
	v_exp_f32_e32 v74, v74
	v_exp_f32_e32 v90, v90
	s_waitcnt lgkmcnt(3)
	v_mfma_f32_32x32x16_bf16 v[48:63], v[148:151], v[132:135], v[48:63]
	v_add_f32_e32 v171, v171, v72
	v_add_f32_e32 v172, v172, v88
	v_add_f32_e32 v171, v171, v73
	v_add_f32_e32 v172, v172, v89
	v_fmamk_f32 v75, v75, 0x3e16c740, v163
	v_fmamk_f32 v91, v91, 0x3e16c740, v163
	v_exp_f32_e32 v75, v75
	v_mfma_f32_32x32x16_bf16 v[0:15], v[184:187], v[104:107], v[0:15]
	v_exp_f32_e32 v91, v91
	v_fmamk_f32 v76, v76, 0x3e16c740, v163
	v_fmamk_f32 v92, v92, 0x3e16c740, v163
	v_exp_f32_e32 v76, v76
	v_exp_f32_e32 v92, v92
	ds_read_b64_tr_b16 v[176:177], v222 offset:0
	ds_read_b64_tr_b16 v[178:179], v222 offset:1536
	ds_read_b64_tr_b16 v[180:181], v222 offset:64
	ds_read_b64_tr_b16 v[182:183], v222 offset:1600
	v_mfma_f32_32x32x16_bf16 v[16:31], v[188:191], v[104:107], v[16:31]
	v_cvt_pk_bf16_f32 v104, v80, v81
	v_cvt_pk_bf16_f32 v105, v82, v83
	v_cvt_pk_bf16_f32 v106, v84, v85
	v_cvt_pk_bf16_f32 v107, v86, v87
	v_add_f32_e32 v171, v171, v74
	v_add_f32_e32 v172, v172, v90
	v_add_f32_e32 v171, v171, v75
	v_add_f32_e32 v172, v172, v91
	v_fmamk_f32 v77, v77, 0x3e16c740, v163
	v_fmamk_f32 v93, v93, 0x3e16c740, v163
	v_exp_f32_e32 v77, v77
	v_exp_f32_e32 v93, v93
	v_mfma_f32_32x32x16_bf16 v[0:15], v[192:195], v[100:103], v[0:15]
	v_fmamk_f32 v78, v78, 0x3e16c740, v163
	v_fmamk_f32 v94, v94, 0x3e16c740, v163
	v_exp_f32_e32 v78, v78
	v_exp_f32_e32 v94, v94
	v_add_f32_e32 v171, v171, v76
	v_add_f32_e32 v172, v172, v92
	v_mfma_f32_32x32x16_bf16 v[16:31], v[196:199], v[100:103], v[16:31]
	v_cvt_pk_bf16_f32 v100, v72, v73
	v_cvt_pk_bf16_f32 v101, v74, v75
	v_add_f32_e32 v171, v171, v77
	v_add_f32_e32 v172, v172, v93
	v_cvt_pk_bf16_f32 v102, v76, v77
	v_fmamk_f32 v79, v79, 0x3e16c740, v163
	v_fmamk_f32 v95, v95, 0x3e16c740, v163
	v_exp_f32_e32 v79, v79
	v_exp_f32_e32 v95, v95
	v_mfma_f32_32x32x16_bf16 v[0:15], v[200:203], v[108:111], v[0:15]
	v_add_f32_e32 v171, v171, v78
	v_add_f32_e32 v172, v172, v94
	v_add_f32_e32 v171, v171, v79
	v_add_f32_e32 v172, v172, v95
	v_cvt_pk_bf16_f32 v103, v78, v79
	v_add_f32_e32 v165, v165, v171
	v_add_f32_e32 v165, v165, v172
	v_mfma_f32_32x32x16_bf16 v[16:31], v[204:207], v[108:111], v[16:31]
	v_cvt_pk_bf16_f32 v108, v88, v89
	v_cvt_pk_bf16_f32 v109, v90, v91
	v_cvt_pk_bf16_f32 v110, v92, v93
	v_cvt_pk_bf16_f32 v111, v94, v95
	s_cmp_lg_u32 s9, 0
	s_cbranch_scc0 .Lamla_noresc_7
	s_nop 15
	v_pk_mul_f32 v[0:1], v[0:1], v[166:167] op_sel_hi:[1,0]
	v_pk_mul_f32 v[2:3], v[2:3], v[166:167] op_sel_hi:[1,0]
	v_pk_mul_f32 v[4:5], v[4:5], v[166:167] op_sel_hi:[1,0]
	v_pk_mul_f32 v[6:7], v[6:7], v[166:167] op_sel_hi:[1,0]
	v_pk_mul_f32 v[8:9], v[8:9], v[166:167] op_sel_hi:[1,0]
	v_pk_mul_f32 v[10:11], v[10:11], v[166:167] op_sel_hi:[1,0]
	v_pk_mul_f32 v[12:13], v[12:13], v[166:167] op_sel_hi:[1,0]
	v_pk_mul_f32 v[14:15], v[14:15], v[166:167] op_sel_hi:[1,0]
	v_pk_mul_f32 v[16:17], v[16:17], v[166:167] op_sel_hi:[1,0]
	v_pk_mul_f32 v[18:19], v[18:19], v[166:167] op_sel_hi:[1,0]
	v_pk_mul_f32 v[20:21], v[20:21], v[166:167] op_sel_hi:[1,0]
	v_pk_mul_f32 v[22:23], v[22:23], v[166:167] op_sel_hi:[1,0]
	v_pk_mul_f32 v[24:25], v[24:25], v[166:167] op_sel_hi:[1,0]
	v_pk_mul_f32 v[26:27], v[26:27], v[166:167] op_sel_hi:[1,0]
	v_pk_mul_f32 v[28:29], v[28:29], v[166:167] op_sel_hi:[1,0]
	v_pk_mul_f32 v[30:31], v[30:31], v[166:167] op_sel_hi:[1,0]
.Lamla_noresc_7:
	s_waitcnt lgkmcnt(0)
	s_barrier
	s_mov_b32 s55, s52
	s_mov_b32 s52, s53
	s_mov_b32 s53, s54
	s_mov_b32 s54, s55
	s_mov_b32 s9, 0
	ds_read_b128 v[136:139], v229 offset:13312
	ds_read_b128 v[140:143], v229 offset:19968
	ds_read_b128 v[144:147], v229 offset:13344
	ds_read_b128 v[148:151], v229 offset:20000
	v_mfma_f32_32x32x16_bf16 v[0:15], v[176:179], v[96:99], v[0:15]
	v_add_u32_e32 v223, s53, v220
	v_add_u32_e32 v224, s54, v221
	v_max3_f32 v168, v32, v33, v34
	v_max3_f32 v170, v48, v49, v50
	ds_read_b64_tr_b16 v[184:185], v222 offset:6144
	ds_read_b64_tr_b16 v[186:187], v222 offset:7680
	ds_read_b64_tr_b16 v[188:189], v222 offset:6208
	ds_read_b64_tr_b16 v[190:191], v222 offset:7744
	v_mfma_f32_32x32x16_bf16 v[16:31], v[180:183], v[96:99], v[16:31]
	v_max3_f32 v168, v168, v35, v36
	v_max3_f32 v170, v170, v51, v52
	v_max3_f32 v168, v168, v37, v38
	v_max3_f32 v170, v170, v53, v54
	v_max3_f32 v168, v168, v39, v40
	v_max3_f32 v170, v170, v55, v56
	ds_read_b64_tr_b16 v[192:193], v222 offset:3072
	ds_read_b64_tr_b16 v[194:195], v222 offset:4608
	ds_read_b64_tr_b16 v[196:197], v222 offset:3136
	ds_read_b64_tr_b16 v[198:199], v222 offset:4672
	s_waitcnt lgkmcnt(11)
	v_mfma_f32_32x32x16_bf16 v[64:79], v[136:139], v[112:115], 0
	v_max3_f32 v168, v168, v41, v42
	v_max3_f32 v170, v170, v57, v58
	v_max3_f32 v168, v168, v43, v44
	v_max3_f32 v170, v170, v59, v60
	v_max3_f32 v168, v168, v45, v46
	v_max3_f32 v170, v170, v61, v62
	v_max_f32_e32 v168, v168, v47
	v_max_f32_e32 v170, v170, v63
	v_max_f32_e32 v168, v168, v170
	ds_read_b128 v[136:139], v229 offset:13376
	ds_read_b64_tr_b16 v[200:201], v222 offset:9216
	ds_read_b64_tr_b16 v[202:203], v222 offset:10752
	ds_read_b64_tr_b16 v[204:205], v222 offset:9280
	ds_read_b64_tr_b16 v[206:207], v222 offset:10816
	s_waitcnt lgkmcnt(15)
	v_mfma_f32_32x32x16_bf16 v[80:95], v[140:143], v[112:115], 0
	v_mov_b32_e32 v170, v168
	s_nop 1
	v_permlane32_swap_b32_e32 v168, v170
	v_max_f32_e32 v168, v168, v170
	v_mul_f32_e32 v168, 0x3e16c740, v168
	v_cmp_gt_f32_e32 vcc, v168, v164
	s_cbranch_vccz .Lamla_nors_8
	v_max_f32_e32 v170, v162, v168
	v_sub_f32_e32 v166, v162, v170
	v_exp_f32_e32 v166, v166
	v_mov_b32_e32 v162, v170
	v_add_f32_e32 v164, 0x41000000, v170
	v_xor_b32_e32 v163, 0x80000000, v170
	v_mul_f32_e32 v165, v165, v166
	s_mov_b32 s9, 1
.Lamla_nors_8:
	v_fmamk_f32 v32, v32, 0x3e16c740, v163
	v_fmamk_f32 v48, v48, 0x3e16c740, v163
	v_exp_f32_e32 v32, v32
	ds_read_b128 v[140:143], v229 offset:20032
	s_waitcnt lgkmcnt(15)
	v_mfma_f32_32x32x16_bf16 v[64:79], v[144:147], v[116:119], v[64:79]
	v_exp_f32_e32 v48, v48
	v_fmamk_f32 v33, v33, 0x3e16c740, v163
	v_fmamk_f32 v49, v49, 0x3e16c740, v163
	v_exp_f32_e32 v33, v33
	v_exp_f32_e32 v49, v49
	ds_read_b128 v[144:147], v229 offset:13408
	s_waitcnt lgkmcnt(15)
	v_mfma_f32_32x32x16_bf16 v[80:95], v[148:151], v[116:119], v[80:95]
	v_fmamk_f32 v34, v34, 0x3e16c740, v163
	v_fmamk_f32 v50, v50, 0x3e16c740, v163
	v_exp_f32_e32 v34, v34
	v_exp_f32_e32 v50, v50
	v_add_f32_e32 v171, v32, v33
	v_add_f32_e32 v172, v48, v49
	v_cvt_pk_bf16_f32 v96, v32, v33
	ds_read_b128 v[148:151], v229 offset:20064
	s_waitcnt lgkmcnt(7)
	v_mfma_f32_32x32x16_bf16 v[64:79], v[136:139], v[120:123], v[64:79]
	v_fmamk_f32 v35, v35, 0x3e16c740, v163
	v_fmamk_f32 v51, v51, 0x3e16c740, v163
	v_exp_f32_e32 v35, v35
	v_exp_f32_e32 v51, v51
	v_fmamk_f32 v36, v36, 0x3e16c740, v163
	v_fmamk_f32 v52, v52, 0x3e16c740, v163
	ds_read_b128 v[136:139], v229 offset:13440
	s_waitcnt lgkmcnt(3)
	v_mfma_f32_32x32x16_bf16 v[80:95], v[140:143], v[120:123], v[80:95]
	v_exp_f32_e32 v36, v36
	v_exp_f32_e32 v52, v52
	v_add_f32_e32 v171, v171, v34
	v_add_f32_e32 v172, v172, v50
	v_add_f32_e32 v171, v171, v35
	v_add_f32_e32 v172, v172, v51
	v_cvt_pk_bf16_f32 v97, v34, v35
	ds_read_b128 v[140:143], v229 offset:20096
	s_waitcnt lgkmcnt(3)
	v_mfma_f32_32x32x16_bf16 v[64:79], v[144:147], v[124:127], v[64:79]
	v_fmamk_f32 v37, v37, 0x3e16c740, v163
	v_fmamk_f32 v53, v53, 0x3e16c740, v163
	v_exp_f32_e32 v37, v37
	v_exp_f32_e32 v53, v53
	v_fmamk_f32 v38, v38, 0x3e16c740, v163
	v_fmamk_f32 v54, v54, 0x3e16c740, v163
	v_exp_f32_e32 v38, v38
	ds_read_b128 v[144:147], v229 offset:13472
	s_waitcnt lgkmcnt(3)
	v_mfma_f32_32x32x16_bf16 v[80:95], v[148:151], v[124:127], v[80:95]
	v_exp_f32_e32 v54, v54
	v_add_f32_e32 v171, v171, v36
	v_add_f32_e32 v172, v172, v52
	v_add_f32_e32 v171, v171, v37
	v_add_f32_e32 v172, v172, v53
	v_cvt_pk_bf16_f32 v98, v36, v37
	v_fmamk_f32 v39, v39, 0x3e16c740, v163
	ds_read_b128 v[148:151], v229 offset:20128
	s_waitcnt lgkmcnt(3)
	v_mfma_f32_32x32x16_bf16 v[64:79], v[136:139], v[128:131], v[64:79]
	v_fmamk_f32 v55, v55, 0x3e16c740, v163
	v_exp_f32_e32 v39, v39
	v_exp_f32_e32 v55, v55
	v_fmamk_f32 v40, v40, 0x3e16c740, v163
	v_fmamk_f32 v56, v56, 0x3e16c740, v163
	v_exp_f32_e32 v40, v40
	s_waitcnt lgkmcnt(2)
	v_mfma_f32_32x32x16_bf16 v[80:95], v[140:143], v[128:131], v[80:95]
	v_exp_f32_e32 v56, v56
	v_add_f32_e32 v171, v171, v38
	v_add_f32_e32 v172, v172, v54
	v_add_f32_e32 v171, v171, v39
	v_add_f32_e32 v172, v172, v55
	v_cvt_pk_bf16_f32 v99, v38, v39
	v_fmamk_f32 v41, v41, 0x3e16c740, v163
	v_fmamk_f32 v57, v57, 0x3e16c740, v163
	s_waitcnt vmcnt(0)
	ds_write_b128 v224, v[156:159]
	s_waitcnt lgkmcnt(2)
	v_mfma_f32_32x32x16_bf16 v[64:79], v[144:147], v[132:135], v[64:79]
	v_exp_f32_e32 v41, v41
	v_exp_f32_e32 v57, v57
	v_fmamk_f32 v42, v42, 0x3e16c740, v163
	v_fmamk_f32 v58, v58, 0x3e16c740, v163
	v_exp_f32_e32 v42, v42
	v_exp_f32_e32 v58, v58
	s_waitcnt lgkmcnt(1)
	v_mfma_f32_32x32x16_bf16 v[80:95], v[148:151], v[132:135], v[80:95]
	v_add_f32_e32 v171, v171, v40
	v_add_f32_e32 v172, v172, v56
	v_add_f32_e32 v171, v171, v41
	v_add_f32_e32 v172, v172, v57
	v_fmamk_f32 v43, v43, 0x3e16c740, v163
	v_fmamk_f32 v59, v59, 0x3e16c740, v163
	v_exp_f32_e32 v43, v43
	v_mfma_f32_32x32x16_bf16 v[0:15], v[184:187], v[104:107], v[0:15]
	v_exp_f32_e32 v59, v59
	v_fmamk_f32 v44, v44, 0x3e16c740, v163
	v_fmamk_f32 v60, v60, 0x3e16c740, v163
	v_exp_f32_e32 v44, v44
	v_exp_f32_e32 v60, v60
	ds_read_b64_tr_b16 v[176:177], v223 offset:0
	ds_read_b64_tr_b16 v[178:179], v223 offset:1536
	ds_read_b64_tr_b16 v[180:181], v223 offset:64
	ds_read_b64_tr_b16 v[182:183], v223 offset:1600
	v_mfma_f32_32x32x16_bf16 v[16:31], v[188:191], v[104:107], v[16:31]
	v_cvt_pk_bf16_f32 v104, v48, v49
	v_cvt_pk_bf16_f32 v105, v50, v51
	v_cvt_pk_bf16_f32 v106, v52, v53
	v_cvt_pk_bf16_f32 v107, v54, v55
	v_add_f32_e32 v171, v171, v42
	v_add_f32_e32 v172, v172, v58
	v_add_f32_e32 v171, v171, v43
	v_add_f32_e32 v172, v172, v59
	v_fmamk_f32 v45, v45, 0x3e16c740, v163
	v_fmamk_f32 v61, v61, 0x3e16c740, v163
	v_exp_f32_e32 v45, v45
	v_exp_f32_e32 v61, v61
	v_mfma_f32_32x32x16_bf16 v[0:15], v[192:195], v[100:103], v[0:15]
	v_fmamk_f32 v46, v46, 0x3e16c740, v163
	v_fmamk_f32 v62, v62, 0x3e16c740, v163
	v_exp_f32_e32 v46, v46
	v_exp_f32_e32 v62, v62
	v_add_f32_e32 v171, v171, v44
	v_add_f32_e32 v172, v172, v60
	v_mfma_f32_32x32x16_bf16 v[16:31], v[196:199], v[100:103], v[16:31]
	v_cvt_pk_bf16_f32 v100, v40, v41
	v_cvt_pk_bf16_f32 v101, v42, v43
	v_add_f32_e32 v171, v171, v45
	v_add_f32_e32 v172, v172, v61
	v_cvt_pk_bf16_f32 v102, v44, v45
	v_fmamk_f32 v47, v47, 0x3e16c740, v163
	v_fmamk_f32 v63, v63, 0x3e16c740, v163
	v_exp_f32_e32 v47, v47
	v_exp_f32_e32 v63, v63
	v_mfma_f32_32x32x16_bf16 v[0:15], v[200:203], v[108:111], v[0:15]
	v_add_f32_e32 v171, v171, v46
	v_add_f32_e32 v172, v172, v62
	v_add_f32_e32 v171, v171, v47
	v_add_f32_e32 v172, v172, v63
	v_cvt_pk_bf16_f32 v103, v46, v47
	v_add_f32_e32 v165, v165, v171
	v_add_f32_e32 v165, v165, v172
	v_mfma_f32_32x32x16_bf16 v[16:31], v[204:207], v[108:111], v[16:31]
	v_cvt_pk_bf16_f32 v108, v56, v57
	v_cvt_pk_bf16_f32 v109, v58, v59
	v_cvt_pk_bf16_f32 v110, v60, v61
	v_cvt_pk_bf16_f32 v111, v62, v63
	s_cmp_lg_u32 s9, 0
	s_cbranch_scc0 .Lamla_noresc_9
	s_nop 15
	v_pk_mul_f32 v[0:1], v[0:1], v[166:167] op_sel_hi:[1,0]
	v_pk_mul_f32 v[2:3], v[2:3], v[166:167] op_sel_hi:[1,0]
	v_pk_mul_f32 v[4:5], v[4:5], v[166:167] op_sel_hi:[1,0]
	v_pk_mul_f32 v[6:7], v[6:7], v[166:167] op_sel_hi:[1,0]
	v_pk_mul_f32 v[8:9], v[8:9], v[166:167] op_sel_hi:[1,0]
	v_pk_mul_f32 v[10:11], v[10:11], v[166:167] op_sel_hi:[1,0]
	v_pk_mul_f32 v[12:13], v[12:13], v[166:167] op_sel_hi:[1,0]
	v_pk_mul_f32 v[14:15], v[14:15], v[166:167] op_sel_hi:[1,0]
	v_pk_mul_f32 v[16:17], v[16:17], v[166:167] op_sel_hi:[1,0]
	v_pk_mul_f32 v[18:19], v[18:19], v[166:167] op_sel_hi:[1,0]
	v_pk_mul_f32 v[20:21], v[20:21], v[166:167] op_sel_hi:[1,0]
	v_pk_mul_f32 v[22:23], v[22:23], v[166:167] op_sel_hi:[1,0]
	v_pk_mul_f32 v[24:25], v[24:25], v[166:167] op_sel_hi:[1,0]
	v_pk_mul_f32 v[26:27], v[26:27], v[166:167] op_sel_hi:[1,0]
	v_pk_mul_f32 v[28:29], v[28:29], v[166:167] op_sel_hi:[1,0]
	v_pk_mul_f32 v[30:31], v[30:31], v[166:167] op_sel_hi:[1,0]
.Lamla_noresc_9:
	s_waitcnt lgkmcnt(0)
	s_barrier
	s_mov_b32 s55, s52
	s_mov_b32 s52, s53
	s_mov_b32 s53, s54
	s_mov_b32 s54, s55
	s_mov_b32 s9, 0
	v_mfma_f32_32x32x16_bf16 v[0:15], v[176:179], v[96:99], v[0:15]
	v_add_u32_e32 v222, s53, v220
	v_max3_f32 v168, v64, v65, v66
	v_max3_f32 v170, v80, v81, v82
	v_max3_f32 v168, v168, v67, v68
	v_max3_f32 v170, v170, v83, v84
	v_max3_f32 v168, v168, v69, v70
	v_max3_f32 v170, v170, v85, v86
	v_max3_f32 v168, v168, v71, v72
	v_max3_f32 v170, v170, v87, v88
	v_max3_f32 v168, v168, v73, v74
	ds_read_b64_tr_b16 v[184:185], v223 offset:6144
	ds_read_b64_tr_b16 v[186:187], v223 offset:7680
	ds_read_b64_tr_b16 v[188:189], v223 offset:6208
	ds_read_b64_tr_b16 v[190:191], v223 offset:7744
	v_mfma_f32_32x32x16_bf16 v[16:31], v[180:183], v[96:99], v[16:31]
	v_max3_f32 v170, v170, v89, v90
	v_max3_f32 v168, v168, v75, v76
	v_max3_f32 v170, v170, v91, v92
	v_max3_f32 v168, v168, v77, v78
	v_max3_f32 v170, v170, v93, v94
	v_max_f32_e32 v168, v168, v79
	v_max_f32_e32 v170, v170, v95
	v_max_f32_e32 v168, v168, v170
	v_mov_b32_e32 v170, v168
	s_nop 1
	v_permlane32_swap_b32_e32 v168, v170
	v_max_f32_e32 v168, v168, v170
	v_mul_f32_e32 v168, 0x3e16c740, v168
	v_cmp_gt_f32_e32 vcc, v168, v164
	s_cbranch_vccz .Lamla_nors_10
	v_max_f32_e32 v170, v162, v168
	v_sub_f32_e32 v166, v162, v170
	v_exp_f32_e32 v166, v166
	v_mov_b32_e32 v162, v170
	v_add_f32_e32 v164, 0x41000000, v170
	v_xor_b32_e32 v163, 0x80000000, v170
	v_mul_f32_e32 v165, v165, v166
	s_mov_b32 s9, 1
.Lamla_nors_10:
	v_fmamk_f32 v64, v64, 0x3e16c740, v163
	v_fmamk_f32 v80, v80, 0x3e16c740, v163
	v_exp_f32_e32 v64, v64
	ds_read_b64_tr_b16 v[192:193], v223 offset:3072
	ds_read_b64_tr_b16 v[194:195], v223 offset:4608
	ds_read_b64_tr_b16 v[196:197], v223 offset:3136
	ds_read_b64_tr_b16 v[198:199], v223 offset:4672
	s_waitcnt lgkmcnt(6)
	v_mfma_f32_32x32x16_bf16 v[0:15], v[184:187], v[104:107], v[0:15]
	v_exp_f32_e32 v80, v80
	v_fmamk_f32 v65, v65, 0x3e16c740, v163
	v_fmamk_f32 v81, v81, 0x3e16c740, v163
	v_exp_f32_e32 v65, v65
	v_exp_f32_e32 v81, v81
	v_fmamk_f32 v66, v66, 0x3e16c740, v163
	v_fmamk_f32 v82, v82, 0x3e16c740, v163
	v_exp_f32_e32 v66, v66
	v_exp_f32_e32 v82, v82
	v_add_f32_e32 v171, v64, v65
	v_add_f32_e32 v172, v80, v81
	v_cvt_pk_bf16_f32 v96, v64, v65
	v_fmamk_f32 v67, v67, 0x3e16c740, v163
	v_fmamk_f32 v83, v83, 0x3e16c740, v163
	v_exp_f32_e32 v67, v67
	v_exp_f32_e32 v83, v83
	ds_read_b64_tr_b16 v[200:201], v223 offset:9216
	ds_read_b64_tr_b16 v[202:203], v223 offset:10752
	ds_read_b64_tr_b16 v[204:205], v223 offset:9280
	ds_read_b64_tr_b16 v[206:207], v223 offset:10816
	s_waitcnt lgkmcnt(8)
	v_mfma_f32_32x32x16_bf16 v[16:31], v[188:191], v[104:107], v[16:31]
	v_cvt_pk_bf16_f32 v104, v80, v81
	v_fmamk_f32 v68, v68, 0x3e16c740, v163
	v_fmamk_f32 v84, v84, 0x3e16c740, v163
	v_exp_f32_e32 v68, v68
	v_exp_f32_e32 v84, v84
	v_add_f32_e32 v171, v171, v66
	v_add_f32_e32 v172, v172, v82
	v_add_f32_e32 v171, v171, v67
	v_add_f32_e32 v172, v172, v83
	v_cvt_pk_bf16_f32 v97, v66, v67
	v_cvt_pk_bf16_f32 v105, v82, v83
	v_fmamk_f32 v69, v69, 0x3e16c740, v163
	v_fmamk_f32 v85, v85, 0x3e16c740, v163
	v_exp_f32_e32 v69, v69
	v_exp_f32_e32 v85, v85
	v_fmamk_f32 v70, v70, 0x3e16c740, v163
	v_fmamk_f32 v86, v86, 0x3e16c740, v163
	v_exp_f32_e32 v70, v70
	v_exp_f32_e32 v86, v86
	s_waitcnt lgkmcnt(6)
	v_mfma_f32_32x32x16_bf16 v[0:15], v[192:195], v[100:103], v[0:15]
	v_add_f32_e32 v171, v171, v68
	v_add_f32_e32 v172, v172, v84
	v_add_f32_e32 v171, v171, v69
	v_add_f32_e32 v172, v172, v85
	v_cvt_pk_bf16_f32 v98, v68, v69
	v_cvt_pk_bf16_f32 v106, v84, v85
	v_fmamk_f32 v71, v71, 0x3e16c740, v163
	v_fmamk_f32 v87, v87, 0x3e16c740, v163
	v_exp_f32_e32 v71, v71
	v_exp_f32_e32 v87, v87
	v_fmamk_f32 v72, v72, 0x3e16c740, v163
	v_fmamk_f32 v88, v88, 0x3e16c740, v163
	v_exp_f32_e32 v72, v72
	v_exp_f32_e32 v88, v88
	v_add_f32_e32 v171, v171, v70
	v_add_f32_e32 v172, v172, v86
	v_add_f32_e32 v171, v171, v71
	v_add_f32_e32 v172, v172, v87
	v_cvt_pk_bf16_f32 v99, v70, v71
	s_waitcnt lgkmcnt(4)
	v_mfma_f32_32x32x16_bf16 v[16:31], v[196:199], v[100:103], v[16:31]
	v_cvt_pk_bf16_f32 v107, v86, v87
	v_fmamk_f32 v73, v73, 0x3e16c740, v163
	v_fmamk_f32 v89, v89, 0x3e16c740, v163
	v_exp_f32_e32 v73, v73
	v_exp_f32_e32 v89, v89
	v_fmamk_f32 v74, v74, 0x3e16c740, v163
	v_fmamk_f32 v90, v90, 0x3e16c740, v163
	v_exp_f32_e32 v74, v74
	v_exp_f32_e32 v90, v90
	v_add_f32_e32 v171, v171, v72
	v_add_f32_e32 v172, v172, v88
	v_add_f32_e32 v171, v171, v73
	v_add_f32_e32 v172, v172, v89
	v_cvt_pk_bf16_f32 v100, v72, v73
	v_fmamk_f32 v75, v75, 0x3e16c740, v163
	v_fmamk_f32 v91, v91, 0x3e16c740, v163
	v_exp_f32_e32 v75, v75
	v_exp_f32_e32 v91, v91
	ds_read_b64_tr_b16 v[176:177], v222 offset:0
	ds_read_b64_tr_b16 v[178:179], v222 offset:1536
	ds_read_b64_tr_b16 v[180:181], v222 offset:64
	ds_read_b64_tr_b16 v[182:183], v222 offset:1600
	s_waitcnt lgkmcnt(6)
	v_mfma_f32_32x32x16_bf16 v[0:15], v[200:203], v[108:111], v[0:15]
	v_fmamk_f32 v76, v76, 0x3e16c740, v163
	v_fmamk_f32 v92, v92, 0x3e16c740, v163
	v_exp_f32_e32 v76, v76
	v_exp_f32_e32 v92, v92
	v_add_f32_e32 v171, v171, v74
	v_add_f32_e32 v172, v172, v90
	v_add_f32_e32 v171, v171, v75
	v_add_f32_e32 v172, v172, v91
	v_cvt_pk_bf16_f32 v101, v74, v75
	v_fmamk_f32 v77, v77, 0x3e16c740, v163
	v_fmamk_f32 v93, v93, 0x3e16c740, v163
	v_exp_f32_e32 v77, v77
	v_exp_f32_e32 v93, v93
	v_fmamk_f32 v78, v78, 0x3e16c740, v163
	v_fmamk_f32 v94, v94, 0x3e16c740, v163
	v_exp_f32_e32 v78, v78
	v_exp_f32_e32 v94, v94
	s_waitcnt lgkmcnt(4)
	v_mfma_f32_32x32x16_bf16 v[16:31], v[204:207], v[108:111], v[16:31]
	v_cvt_pk_bf16_f32 v108, v88, v89
	v_cvt_pk_bf16_f32 v109, v90, v91
	v_add_f32_e32 v171, v171, v76
	v_add_f32_e32 v172, v172, v92
	v_add_f32_e32 v171, v171, v77
	v_add_f32_e32 v172, v172, v93
	v_cvt_pk_bf16_f32 v102, v76, v77
	v_cvt_pk_bf16_f32 v110, v92, v93
	v_fmamk_f32 v79, v79, 0x3e16c740, v163
	v_fmamk_f32 v95, v95, 0x3e16c740, v163
	v_exp_f32_e32 v79, v79
	v_exp_f32_e32 v95, v95
	v_add_f32_e32 v171, v171, v78
	v_add_f32_e32 v172, v172, v94
	v_add_f32_e32 v171, v171, v79
	v_add_f32_e32 v172, v172, v95
	v_cvt_pk_bf16_f32 v103, v78, v79
	v_cvt_pk_bf16_f32 v111, v94, v95
	v_add_f32_e32 v165, v165, v171
	v_add_f32_e32 v165, v165, v172
	s_cmp_lg_u32 s9, 0
	s_cbranch_scc0 .Lamla_noresc_11
	s_nop 15
	v_pk_mul_f32 v[0:1], v[0:1], v[166:167] op_sel_hi:[1,0]
	v_pk_mul_f32 v[2:3], v[2:3], v[166:167] op_sel_hi:[1,0]
	v_pk_mul_f32 v[4:5], v[4:5], v[166:167] op_sel_hi:[1,0]
	v_pk_mul_f32 v[6:7], v[6:7], v[166:167] op_sel_hi:[1,0]
	v_pk_mul_f32 v[8:9], v[8:9], v[166:167] op_sel_hi:[1,0]
	v_pk_mul_f32 v[10:11], v[10:11], v[166:167] op_sel_hi:[1,0]
	v_pk_mul_f32 v[12:13], v[12:13], v[166:167] op_sel_hi:[1,0]
	v_pk_mul_f32 v[14:15], v[14:15], v[166:167] op_sel_hi:[1,0]
	v_pk_mul_f32 v[16:17], v[16:17], v[166:167] op_sel_hi:[1,0]
	v_pk_mul_f32 v[18:19], v[18:19], v[166:167] op_sel_hi:[1,0]
	v_pk_mul_f32 v[20:21], v[20:21], v[166:167] op_sel_hi:[1,0]
	v_pk_mul_f32 v[22:23], v[22:23], v[166:167] op_sel_hi:[1,0]
	v_pk_mul_f32 v[24:25], v[24:25], v[166:167] op_sel_hi:[1,0]
	v_pk_mul_f32 v[26:27], v[26:27], v[166:167] op_sel_hi:[1,0]
	v_pk_mul_f32 v[28:29], v[28:29], v[166:167] op_sel_hi:[1,0]
	v_pk_mul_f32 v[30:31], v[30:31], v[166:167] op_sel_hi:[1,0]

; #define AT_GLOADK(k0) do { kreg = *(const u32x4*)(Kb + (size_t)((k0) + (tid >> 3)) * 64 + (tid & 7) * 8); \
;             if (MLA) preg = *(const u32x2*)(Pb + (size_t)((k0) + (tid >> 3)) * 32 + (tid & 7) * 4); } while (0)
; #define AT_GLOADV(k0) do { vreg = *(const u32x4*)(Vb + (size_t)((k0) + (tid >> 3)) * 64 + (tid & 7) * 8); } while (0)
; #define AT_WRITEK(buf) do { *(LAS u32x4*)(lds + (buf) * KBUF + (tid >> 3) * KSTR + (tid & 7) * 16) = kreg; \
;             if (MLA) *(LAS u32x2*)(lds + (buf) * KBUF + (tid >> 3) * KSTR + 128 + (tid & 7) * 8) = preg; } while (0)
; #define AT_WRITEV(buf) do { *(LAS u32x4*)(lds + 2 * KBUF + (buf) * VBUF + (tid >> 3) * VSTR + (tid & 7) * 16) = vreg; } while (0)
; #define AT_STEP(SC0, SC1, SN0, SN1, t, DOK, DOV) do { \
;             if (DOK) AT_GLOADK(((t) + 2) * 64); \
;             if (DOV) { AT_GLOADV(((t) + 1) * 64); AT_QK(SN0, SN1, ((t) + 1) & 1); } \
;             AT_SMPV(SC0, SC1, (t) & 1); \
;             if (DOK) AT_WRITEK((t) & 1); \
;             if (DOV) AT_WRITEV(((t) + 1) & 1); \
;             __syncthreads(); } while (0)
; template <bool MLA>
; DI void attn_phase(const int TID, const int BID, LAS unsigned char* lds, const Params& p, bool need_ctx) {
;     ...
;         AT_GLOADK(0); AT_GLOADV(0); AT_WRITEK(0); AT_WRITEV(0);
;         AT_GLOADK(64); AT_WRITEK(1);
;         __syncthreads();
;         AT_QK(sa0, sa1, 0);
;         __syncthreads();
;         int t = 0;
;         for (; t < ntile - 2; t += 2) {
;             AT_STEP(sa0, sa1, sb0, sb1, t, true, true);
;             AT_STEP(sb0, sb1, sa0, sa1, t + 1, true, true);
;         }
;         AT_STEP(sa0, sa1, sb0, sb1, t, false, true);
;         AT_STEP(sb0, sb1, sa0, sa1, t + 1, false, false);
.Lamla_done:
	s_branch .LBB0_317
.LBB0_317:
	s_mov_b64 s[4:5], 0
